# speedup vs baseline: 1.0101x; 1.0025x over previous
;   #define STAGE(P,BASE,LD,br,kt) do{long _g=(long)(br)*LD+(long)(kt)*BK; \
;     _Pragma("unroll") for(int _i=0;_i<2;++_i){ \
;       __builtin_amdgcn_global_load_lds((const unsigned*)(BASE+_g+(long)sR[_i]*LD+sC[_i]), \
;         LDSP(unsigned,(char*)(P)+wid*1024+_i*8192),16,0,0);}}while(0)
;   #define LDA(dst,b,h) _Pragma("unroll") for(int m=0;m<4;++m) _Pragma("unroll") for(int k=0;k<2;++k) \
;     dst[m][k]=*reinterpret_cast<const s16x8*>((char*)SA(b,h)+lds_byte8(wr*64+m*16+fr,k*32+fq*8))
;   #define LDB(dst,b,h) _Pragma("unroll") for(int n=0;n<2;++n) _Pragma("unroll") for(int k=0;k<2;++k) \
;     dst[n][k]=*reinterpret_cast<const s16x8*>((char*)SB(b,h)+lds_byte8(wc*32+n*16+fr,k*32+fq*8))
;   #define MMA(ai,bj,At,Bt) do{__builtin_amdgcn_s_setprio(1); \
;     _Pragma("unroll") for(int m=0;m<4;++m) _Pragma("unroll") for(int n=0;n<2;++n) _Pragma("unroll") for(int k=0;k<2;++k) \
;       acc[ai][bj][m][n]=__builtin_amdgcn_mfma_f32_16x16x32_bf16(Bt[n][k],At[m][k],acc[ai][bj][m][n],0,0,0); \
;     __builtin_amdgcn_s_setprio(0);}while(0)
;   #define WAIT_V(n) asm volatile("s_waitcnt vmcnt(" #n ")":::"memory")
;   #define WAIT_L(n) asm volatile("s_waitcnt lgkmcnt(" #n ")":::"memory")
;   #define BAR __builtin_amdgcn_s_barrier()
;   #define SCHED __builtin_amdgcn_sched_barrier(0)
; template <class Epi>
; __device__ __forceinline__ void gemm_tile8(const u16* __restrict__ A, long lda, const u16* __restrict__ Bt, long ldb, int K, char* shmc, Epi epi){
;     ...
;   for(int t=0;t<nt-2;t+=2){
;     LDB(B0,0,0); SCHED; LDA(At,0,0); STAGE(SA(1,1),A,lda,brow+HALF,t+1);
;     WAIT_L(8); BAR; WAIT_L(0); MMA(0,0,At,B0); BAR; SCHED;
;     LDB(B1,0,1); STAGE(SB(0,0),Bt,ldb,bcol,t+2);
;     BAR; WAIT_L(0); MMA(0,1,At,B1); BAR;
;     LDA(At,0,1); STAGE(SA(0,0),A,lda,brow,t+2);
;     BAR; WAIT_L(0); MMA(1,0,At,B0); BAR; SCHED;
;     STAGE(SB(0,1),Bt,ldb,bcol+HALF,t+2);
;     WAIT_V(6); BAR; MMA(1,1,At,B1); BAR;
.LBB0_52:
	ds_read_b128 v[156:159], v152
	ds_read_b128 v[160:163], v152 offset:1024
	ds_read_b128 v[164:167], v152 offset:2048
	ds_read_b128 v[168:171], v152 offset:3072
	v_lshl_add_u64 v[234:235], v[142:143], 0, s[12:13]
	s_mov_b32 m0, s35
	v_add_u32_e32 v153, s30, v151
	v_add_u32_e32 v154, s31, v151
	v_add_u32_e32 v155, s34, v151
	v_lshl_add_u64 v[218:219], v[234:235], 0, s[36:37]
	v_lshl_add_u64 v[236:237], v[144:145], 0, s[12:13]
	ds_read_b128 v[172:175], v147
	ds_read_b128 v[176:179], v147 offset:1024
	ds_read_b128 v[180:183], v153
	ds_read_b128 v[184:187], v153 offset:1024
	ds_read_b128 v[188:191], v154
	ds_read_b128 v[192:195], v154 offset:1024
	ds_read_b128 v[196:199], v155
	ds_read_b128 v[200:203], v155 offset:1024
	global_load_lds_dwordx4 v[218:219], off
	v_lshl_add_u64 v[218:219], v[236:237], 0, s[36:37]
	s_mov_b32 m0, s14
	s_nop 0
	global_load_lds_dwordx4 v[218:219], off
	s_waitcnt lgkmcnt(8)
	s_barrier
	s_waitcnt lgkmcnt(0)
	s_waitcnt lgkmcnt(0)
	v_mfma_f32_16x16x32_bf16 v[126:129], v[156:159], v[172:175], v[126:129]
	v_mfma_f32_16x16x32_bf16 v[122:125], v[164:167], v[172:175], v[122:125]
	v_mfma_f32_16x16x32_bf16 v[118:121], v[156:159], v[180:183], v[118:121]
	v_mfma_f32_16x16x32_bf16 v[114:117], v[164:167], v[180:183], v[114:117]
	v_mfma_f32_16x16x32_bf16 v[110:113], v[156:159], v[188:191], v[110:113]
	v_mfma_f32_16x16x32_bf16 v[106:109], v[164:167], v[188:191], v[106:109]
	v_mfma_f32_16x16x32_bf16 v[102:105], v[156:159], v[196:199], v[102:105]
	v_mfma_f32_16x16x32_bf16 v[98:101], v[164:167], v[196:199], v[98:101]
	v_mfma_f32_16x16x32_bf16 v[126:129], v[160:163], v[176:179], v[126:129]
	v_mfma_f32_16x16x32_bf16 v[122:125], v[168:171], v[176:179], v[122:125]
	v_mfma_f32_16x16x32_bf16 v[118:121], v[160:163], v[184:187], v[118:121]
	v_mfma_f32_16x16x32_bf16 v[114:117], v[168:171], v[184:187], v[114:117]
	v_mfma_f32_16x16x32_bf16 v[110:113], v[160:163], v[192:195], v[110:113]
	v_mfma_f32_16x16x32_bf16 v[106:109], v[168:171], v[192:195], v[106:109]
	v_mfma_f32_16x16x32_bf16 v[102:105], v[160:163], v[200:203], v[102:105]
	v_mfma_f32_16x16x32_bf16 v[98:101], v[168:171], v[200:203], v[98:101]
	s_barrier
	v_lshl_add_u64 v[238:239], v[138:139], 0, s[12:13]
	s_mov_b32 m0, s19
	v_lshl_add_u64 v[240:241], v[238:239], 0, s[38:39]
	ds_read_b128 v[218:221], v150
	ds_read_b128 v[222:225], v150 offset:1024
	ds_read_b128 v[226:229], v150 offset:2048
	ds_read_b128 v[230:233], v150 offset:3072
	global_load_lds_dwordx4 v[240:241], off
	v_lshl_add_u64 v[240:241], v[140:141], 0, s[12:13]
	v_lshl_add_u64 v[242:243], v[240:241], 0, s[38:39]
	s_mov_b32 m0, s20
	s_nop 0
	global_load_lds_dwordx4 v[242:243], off
	s_barrier
	s_waitcnt lgkmcnt(0)
	s_waitcnt lgkmcnt(0)
	v_mfma_f32_16x16x32_bf16 v[94:97], v[218:221], v[172:175], v[94:97]
	v_mfma_f32_16x16x32_bf16 v[90:93], v[226:229], v[172:175], v[90:93]
	v_mfma_f32_16x16x32_bf16 v[86:89], v[218:221], v[180:183], v[86:89]
	v_mfma_f32_16x16x32_bf16 v[82:85], v[226:229], v[180:183], v[82:85]
	v_mfma_f32_16x16x32_bf16 v[78:81], v[218:221], v[188:191], v[78:81]
	v_mfma_f32_16x16x32_bf16 v[74:77], v[226:229], v[188:191], v[74:77]
	v_mfma_f32_16x16x32_bf16 v[70:73], v[218:221], v[196:199], v[70:73]
	v_mfma_f32_16x16x32_bf16 v[66:69], v[226:229], v[196:199], v[66:69]
	v_mfma_f32_16x16x32_bf16 v[94:97], v[222:225], v[176:179], v[94:97]
	v_mfma_f32_16x16x32_bf16 v[90:93], v[230:233], v[176:179], v[90:93]
	v_mfma_f32_16x16x32_bf16 v[86:89], v[222:225], v[184:187], v[86:89]
	v_mfma_f32_16x16x32_bf16 v[82:85], v[230:233], v[184:187], v[82:85]
	v_mfma_f32_16x16x32_bf16 v[78:81], v[222:225], v[192:195], v[78:81]
	v_mfma_f32_16x16x32_bf16 v[74:77], v[230:233], v[192:195], v[74:77]
	v_mfma_f32_16x16x32_bf16 v[70:73], v[222:225], v[200:203], v[70:73]
	v_mfma_f32_16x16x32_bf16 v[66:69], v[230:233], v[200:203], v[66:69]
	s_mov_b32 m0, s18
	v_lshl_add_u64 v[242:243], v[234:235], 0, s[38:39]
	s_barrier
	ds_read_b128 v[172:175], v147 offset:16384
	ds_read_b128 v[176:179], v147 offset:17408
	ds_read_b128 v[180:183], v153 offset:16384
	ds_read_b128 v[184:187], v153 offset:17408
	ds_read_b128 v[188:191], v154 offset:16384
	ds_read_b128 v[192:195], v154 offset:17408
	ds_read_b128 v[196:199], v155 offset:16384
	ds_read_b128 v[200:203], v155 offset:17408
	global_load_lds_dwordx4 v[242:243], off
	v_lshl_add_u64 v[242:243], v[236:237], 0, s[38:39]
	s_mov_b32 m0, s21
	s_nop 0
	global_load_lds_dwordx4 v[242:243], off
	s_barrier
	s_waitcnt lgkmcnt(0)
	s_waitcnt lgkmcnt(0)
	v_mfma_f32_16x16x32_bf16 v[62:65], v[156:159], v[172:175], v[62:65]
	v_mfma_f32_16x16x32_bf16 v[58:61], v[164:167], v[172:175], v[58:61]
	v_mfma_f32_16x16x32_bf16 v[54:57], v[156:159], v[180:183], v[54:57]
	v_mfma_f32_16x16x32_bf16 v[50:53], v[164:167], v[180:183], v[50:53]
	v_mfma_f32_16x16x32_bf16 v[46:49], v[156:159], v[188:191], v[46:49]
	v_mfma_f32_16x16x32_bf16 v[42:45], v[164:167], v[188:191], v[42:45]
	v_mfma_f32_16x16x32_bf16 v[38:41], v[156:159], v[196:199], v[38:41]
	v_mfma_f32_16x16x32_bf16 v[34:37], v[164:167], v[196:199], v[34:37]
	v_mfma_f32_16x16x32_bf16 v[62:65], v[160:163], v[176:179], v[62:65]
	v_mfma_f32_16x16x32_bf16 v[58:61], v[168:171], v[176:179], v[58:61]
	v_mfma_f32_16x16x32_bf16 v[54:57], v[160:163], v[184:187], v[54:57]
	v_mfma_f32_16x16x32_bf16 v[50:53], v[168:171], v[184:187], v[50:53]
	v_mfma_f32_16x16x32_bf16 v[46:49], v[160:163], v[192:195], v[46:49]
	v_mfma_f32_16x16x32_bf16 v[42:45], v[168:171], v[192:195], v[42:45]
	v_mfma_f32_16x16x32_bf16 v[38:41], v[160:163], v[200:203], v[38:41]
	v_mfma_f32_16x16x32_bf16 v[34:37], v[168:171], v[200:203], v[34:37]
	s_barrier
;   #define STAGE(P,BASE,LD,br,kt) do{long _g=(long)(br)*LD+(long)(kt)*BK; \
;     _Pragma("unroll") for(int _i=0;_i<2;++_i){ \
;       __builtin_amdgcn_global_load_lds((const unsigned*)(BASE+_g+(long)sR[_i]*LD+sC[_i]), \
;         LDSP(unsigned,(char*)(P)+wid*1024+_i*8192),16,0,0);}}while(0)
;   #define LDA(dst,b,h) _Pragma("unroll") for(int m=0;m<4;++m) _Pragma("unroll") for(int k=0;k<2;++k) \
;     dst[m][k]=*reinterpret_cast<const s16x8*>((char*)SA(b,h)+lds_byte8(wr*64+m*16+fr,k*32+fq*8))
;   #define LDB(dst,b,h) _Pragma("unroll") for(int n=0;n<2;++n) _Pragma("unroll") for(int k=0;k<2;++k) \
;     dst[n][k]=*reinterpret_cast<const s16x8*>((char*)SB(b,h)+lds_byte8(wc*32+n*16+fr,k*32+fq*8))
;   #define MMA(ai,bj,At,Bt) do{__builtin_amdgcn_s_setprio(1); \
;     _Pragma("unroll") for(int m=0;m<4;++m) _Pragma("unroll") for(int n=0;n<2;++n) _Pragma("unroll") for(int k=0;k<2;++k) \
;       acc[ai][bj][m][n]=__builtin_amdgcn_mfma_f32_16x16x32_bf16(Bt[n][k],At[m][k],acc[ai][bj][m][n],0,0,0); \
;     __builtin_amdgcn_s_setprio(0);}while(0)
;   #define WAIT_V(n) asm volatile("s_waitcnt vmcnt(" #n ")":::"memory")
;   #define WAIT_L(n) asm volatile("s_waitcnt lgkmcnt(" #n ")":::"memory")
;   #define BAR __builtin_amdgcn_s_barrier()
;   #define SCHED __builtin_amdgcn_sched_barrier(0)
; template <class Epi>
; __device__ __forceinline__ void gemm_tile8(const u16* __restrict__ A, long lda, const u16* __restrict__ Bt, long ldb, int K, char* shmc, Epi epi){
;     ...
;     STAGE(SB(0,1),Bt,ldb,bcol+HALF,t+2);
;     WAIT_V(6); BAR; MMA(1,1,At,B1); BAR;
;     LDB(B0,1,0); SCHED; LDA(At,1,0); STAGE(SA(0,1),A,lda,brow+HALF,t+2);
;     WAIT_L(8); BAR; WAIT_L(0); MMA(0,0,At,B0); BAR; SCHED;
;     LDB(B1,1,1); STAGE(SB(1,0),Bt,ldb,bcol,t+3);
;     BAR; WAIT_L(0); MMA(0,1,At,B1); BAR;
;     LDA(At,1,1); STAGE(SA(1,0),A,lda,brow,t+3);
;     BAR; WAIT_L(0); MMA(1,0,At,B0); BAR; SCHED;
	s_mov_b32 m0, s22
	v_lshl_add_u64 v[156:157], v[238:239], 0, s[40:41]
	global_load_lds_dwordx4 v[156:157], off
	v_lshl_add_u64 v[156:157], v[240:241], 0, s[40:41]
	s_mov_b32 m0, s23
	s_nop 0
	global_load_lds_dwordx4 v[156:157], off
	s_waitcnt vmcnt(6)
	s_barrier
	v_mfma_f32_16x16x32_bf16 v[28:31], v[218:221], v[172:175], v[28:31]
	v_mfma_f32_16x16x32_bf16 v[24:27], v[226:229], v[172:175], v[24:27]
	v_mfma_f32_16x16x32_bf16 v[20:23], v[218:221], v[180:183], v[20:23]
	v_mfma_f32_16x16x32_bf16 v[16:19], v[226:229], v[180:183], v[16:19]
	v_mfma_f32_16x16x32_bf16 v[12:15], v[218:221], v[188:191], v[12:15]
	v_mfma_f32_16x16x32_bf16 v[8:11], v[226:229], v[188:191], v[8:11]
	v_mfma_f32_16x16x32_bf16 v[4:7], v[218:221], v[196:199], v[4:7]
	v_mfma_f32_16x16x32_bf16 v[0:3], v[226:229], v[196:199], v[0:3]
	v_mfma_f32_16x16x32_bf16 v[28:31], v[222:225], v[176:179], v[28:31]
	v_mfma_f32_16x16x32_bf16 v[24:27], v[230:233], v[176:179], v[24:27]
	v_mfma_f32_16x16x32_bf16 v[20:23], v[222:225], v[184:187], v[20:23]
	v_mfma_f32_16x16x32_bf16 v[16:19], v[230:233], v[184:187], v[16:19]
	v_mfma_f32_16x16x32_bf16 v[12:15], v[222:225], v[192:195], v[12:15]
	v_mfma_f32_16x16x32_bf16 v[8:11], v[230:233], v[192:195], v[8:11]
	v_mfma_f32_16x16x32_bf16 v[4:7], v[222:225], v[200:203], v[4:7]
	v_mfma_f32_16x16x32_bf16 v[0:3], v[230:233], v[200:203], v[0:3]
	s_barrier
	ds_read_b128 v[156:159], v149
	ds_read_b128 v[160:163], v149 offset:1024
	ds_read_b128 v[164:167], v149 offset:2048
	ds_read_b128 v[168:171], v149 offset:3072
	s_mov_b32 m0, s24
	v_lshl_add_u64 v[218:219], v[234:235], 0, s[40:41]
	ds_read_b128 v[172:175], v147 offset:32768
	ds_read_b128 v[176:179], v147 offset:33792
	ds_read_b128 v[180:183], v153 offset:32768
	ds_read_b128 v[184:187], v153 offset:33792
	ds_read_b128 v[188:191], v154 offset:32768
	ds_read_b128 v[192:195], v154 offset:33792
	ds_read_b128 v[196:199], v155 offset:32768
	ds_read_b128 v[200:203], v155 offset:33792
	global_load_lds_dwordx4 v[218:219], off
	v_lshl_add_u64 v[218:219], v[236:237], 0, s[40:41]
	s_mov_b32 m0, s25
	s_nop 0
	global_load_lds_dwordx4 v[218:219], off
	s_waitcnt lgkmcnt(8)
	s_barrier
	s_waitcnt lgkmcnt(0)
	s_waitcnt lgkmcnt(0)
	v_mfma_f32_16x16x32_bf16 v[126:129], v[156:159], v[172:175], v[126:129]
	v_mfma_f32_16x16x32_bf16 v[122:125], v[164:167], v[172:175], v[122:125]
	v_mfma_f32_16x16x32_bf16 v[118:121], v[156:159], v[180:183], v[118:121]
	v_mfma_f32_16x16x32_bf16 v[114:117], v[164:167], v[180:183], v[114:117]
	v_mfma_f32_16x16x32_bf16 v[110:113], v[156:159], v[188:191], v[110:113]
	v_mfma_f32_16x16x32_bf16 v[106:109], v[164:167], v[188:191], v[106:109]
	v_mfma_f32_16x16x32_bf16 v[102:105], v[156:159], v[196:199], v[102:105]
	v_mfma_f32_16x16x32_bf16 v[98:101], v[164:167], v[196:199], v[98:101]
	v_mfma_f32_16x16x32_bf16 v[126:129], v[160:163], v[176:179], v[126:129]
	v_mfma_f32_16x16x32_bf16 v[122:125], v[168:171], v[176:179], v[122:125]
	v_mfma_f32_16x16x32_bf16 v[118:121], v[160:163], v[184:187], v[118:121]
	v_mfma_f32_16x16x32_bf16 v[114:117], v[168:171], v[184:187], v[114:117]
	v_mfma_f32_16x16x32_bf16 v[110:113], v[160:163], v[192:195], v[110:113]
	v_mfma_f32_16x16x32_bf16 v[106:109], v[168:171], v[192:195], v[106:109]
	v_mfma_f32_16x16x32_bf16 v[102:105], v[160:163], v[200:203], v[102:105]
	v_mfma_f32_16x16x32_bf16 v[98:101], v[168:171], v[200:203], v[98:101]
	s_barrier
	s_mov_b32 m0, s26
	v_lshl_add_u64 v[242:243], v[238:239], 0, s[42:43]
	ds_read_b128 v[218:221], v148
	ds_read_b128 v[222:225], v148 offset:1024
	ds_read_b128 v[226:229], v148 offset:2048
	ds_read_b128 v[230:233], v148 offset:3072
	global_load_lds_dwordx4 v[242:243], off
	v_lshl_add_u64 v[242:243], v[240:241], 0, s[42:43]
	s_mov_b32 m0, s27
	s_nop 0
	global_load_lds_dwordx4 v[242:243], off
	s_barrier
	s_waitcnt lgkmcnt(0)
	s_waitcnt lgkmcnt(0)
	v_mfma_f32_16x16x32_bf16 v[94:97], v[218:221], v[172:175], v[94:97]
	v_mfma_f32_16x16x32_bf16 v[90:93], v[226:229], v[172:175], v[90:93]
	v_mfma_f32_16x16x32_bf16 v[86:89], v[218:221], v[180:183], v[86:89]
	v_mfma_f32_16x16x32_bf16 v[82:85], v[226:229], v[180:183], v[82:85]
	v_mfma_f32_16x16x32_bf16 v[78:81], v[218:221], v[188:191], v[78:81]
	v_mfma_f32_16x16x32_bf16 v[74:77], v[226:229], v[188:191], v[74:77]
	v_mfma_f32_16x16x32_bf16 v[70:73], v[218:221], v[196:199], v[70:73]
	v_mfma_f32_16x16x32_bf16 v[66:69], v[226:229], v[196:199], v[66:69]
	v_mfma_f32_16x16x32_bf16 v[94:97], v[222:225], v[176:179], v[94:97]
	v_mfma_f32_16x16x32_bf16 v[90:93], v[230:233], v[176:179], v[90:93]
	v_mfma_f32_16x16x32_bf16 v[86:89], v[222:225], v[184:187], v[86:89]
	v_mfma_f32_16x16x32_bf16 v[82:85], v[230:233], v[184:187], v[82:85]
	v_mfma_f32_16x16x32_bf16 v[78:81], v[222:225], v[192:195], v[78:81]
	v_mfma_f32_16x16x32_bf16 v[74:77], v[230:233], v[192:195], v[74:77]
	v_mfma_f32_16x16x32_bf16 v[70:73], v[222:225], v[200:203], v[70:73]
	v_mfma_f32_16x16x32_bf16 v[66:69], v[230:233], v[200:203], v[66:69]
	s_mov_b32 m0, s28
	v_lshl_add_u64 v[234:235], v[234:235], 0, s[42:43]
	s_barrier
	ds_read_b128 v[172:175], v147 offset:49152
	ds_read_b128 v[176:179], v147 offset:50176
	ds_read_b128 v[180:183], v153 offset:49152
	ds_read_b128 v[184:187], v153 offset:50176
	ds_read_b128 v[188:191], v154 offset:49152
	ds_read_b128 v[192:195], v154 offset:50176
	ds_read_b128 v[196:199], v155 offset:49152
	ds_read_b128 v[200:203], v155 offset:50176
	global_load_lds_dwordx4 v[234:235], off
	v_lshl_add_u64 v[234:235], v[236:237], 0, s[42:43]
	s_mov_b32 m0, s29
	s_nop 0
	global_load_lds_dwordx4 v[234:235], off
	s_barrier
;   #define STAGE(P,BASE,LD,br,kt) do{long _g=(long)(br)*LD+(long)(kt)*BK; \
;     _Pragma("unroll") for(int _i=0;_i<2;++_i){ \
;       __builtin_amdgcn_global_load_lds((const unsigned*)(BASE+_g+(long)sR[_i]*LD+sC[_i]), \
;         LDSP(unsigned,(char*)(P)+wid*1024+_i*8192),16,0,0);}}while(0)
;   #define LDA(dst,b,h) _Pragma("unroll") for(int m=0;m<4;++m) _Pragma("unroll") for(int k=0;k<2;++k) \
;     dst[m][k]=*reinterpret_cast<const s16x8*>((char*)SA(b,h)+lds_byte8(wr*64+m*16+fr,k*32+fq*8))
;   #define LDB(dst,b,h) _Pragma("unroll") for(int n=0;n<2;++n) _Pragma("unroll") for(int k=0;k<2;++k) \
;     dst[n][k]=*reinterpret_cast<const s16x8*>((char*)SB(b,h)+lds_byte8(wc*32+n*16+fr,k*32+fq*8))
;   #define MMA(ai,bj,At,Bt) do{__builtin_amdgcn_s_setprio(1); \
;     _Pragma("unroll") for(int m=0;m<4;++m) _Pragma("unroll") for(int n=0;n<2;++n) _Pragma("unroll") for(int k=0;k<2;++k) \
;       acc[ai][bj][m][n]=__builtin_amdgcn_mfma_f32_16x16x32_bf16(Bt[n][k],At[m][k],acc[ai][bj][m][n],0,0,0); \
;     __builtin_amdgcn_s_setprio(0);}while(0)
;   #define WAIT_V(n) asm volatile("s_waitcnt vmcnt(" #n ")":::"memory")
;   #define WAIT_L(n) asm volatile("s_waitcnt lgkmcnt(" #n ")":::"memory")
;   #define BAR __builtin_amdgcn_s_barrier()
; template <class Epi>
; __device__ __forceinline__ void gemm_tile8(const u16* __restrict__ A, long lda, const u16* __restrict__ Bt, long ldb, int K, char* shmc, Epi epi){
;     ...
;     STAGE(SB(1,1),Bt,ldb,bcol+HALF,t+3);
;     WAIT_V(6); BAR; MMA(1,1,At,B1); BAR;
;   }
;   { LDB(B0,0,0); LDA(At,0,0); STAGE(SA(1,1),A,lda,brow+HALF,nt-1);
;     BAR; WAIT_L(0); MMA(0,0,At,B0); BAR;
;     LDB(B1,0,1); BAR; WAIT_L(0); MMA(0,1,At,B1); BAR;
;     LDA(At,0,1); WAIT_V(4); BAR; WAIT_L(0); MMA(1,0,At,B0); MMA(1,1,At,B1); BAR; }
	s_waitcnt lgkmcnt(0)
	s_waitcnt lgkmcnt(0)
	v_mfma_f32_16x16x32_bf16 v[62:65], v[156:159], v[172:175], v[62:65]
	v_mfma_f32_16x16x32_bf16 v[58:61], v[164:167], v[172:175], v[58:61]
	v_mfma_f32_16x16x32_bf16 v[54:57], v[156:159], v[180:183], v[54:57]
	v_mfma_f32_16x16x32_bf16 v[50:53], v[164:167], v[180:183], v[50:53]
	v_mfma_f32_16x16x32_bf16 v[46:49], v[156:159], v[188:191], v[46:49]
	v_mfma_f32_16x16x32_bf16 v[42:45], v[164:167], v[188:191], v[42:45]
	v_mfma_f32_16x16x32_bf16 v[38:41], v[156:159], v[196:199], v[38:41]
	v_mfma_f32_16x16x32_bf16 v[34:37], v[164:167], v[196:199], v[34:37]
	v_mfma_f32_16x16x32_bf16 v[62:65], v[160:163], v[176:179], v[62:65]
	v_mfma_f32_16x16x32_bf16 v[58:61], v[168:171], v[176:179], v[58:61]
	v_mfma_f32_16x16x32_bf16 v[54:57], v[160:163], v[184:187], v[54:57]
	v_mfma_f32_16x16x32_bf16 v[50:53], v[168:171], v[184:187], v[50:53]
	v_mfma_f32_16x16x32_bf16 v[46:49], v[160:163], v[192:195], v[46:49]
	v_mfma_f32_16x16x32_bf16 v[42:45], v[168:171], v[192:195], v[42:45]
	v_mfma_f32_16x16x32_bf16 v[38:41], v[160:163], v[200:203], v[38:41]
	v_mfma_f32_16x16x32_bf16 v[34:37], v[168:171], v[200:203], v[34:37]
	s_barrier
	s_mov_b32 m0, s16
	v_lshl_add_u64 v[156:157], v[238:239], 0, s[44:45]
	global_load_lds_dwordx4 v[156:157], off
	v_lshl_add_u64 v[156:157], v[240:241], 0, s[44:45]
	s_mov_b32 m0, s17
	s_nop 0
	global_load_lds_dwordx4 v[156:157], off
	s_waitcnt vmcnt(6)
	s_barrier
	v_mfma_f32_16x16x32_bf16 v[28:31], v[218:221], v[172:175], v[28:31]
	v_mfma_f32_16x16x32_bf16 v[24:27], v[226:229], v[172:175], v[24:27]
	v_mfma_f32_16x16x32_bf16 v[20:23], v[218:221], v[180:183], v[20:23]
	v_mfma_f32_16x16x32_bf16 v[16:19], v[226:229], v[180:183], v[16:19]
	v_mfma_f32_16x16x32_bf16 v[12:15], v[218:221], v[188:191], v[12:15]
	v_mfma_f32_16x16x32_bf16 v[8:11], v[226:229], v[188:191], v[8:11]
	v_mfma_f32_16x16x32_bf16 v[4:7], v[218:221], v[196:199], v[4:7]
	v_mfma_f32_16x16x32_bf16 v[0:3], v[226:229], v[196:199], v[0:3]
	v_mfma_f32_16x16x32_bf16 v[28:31], v[222:225], v[176:179], v[28:31]
	v_mfma_f32_16x16x32_bf16 v[24:27], v[230:233], v[176:179], v[24:27]
	v_mfma_f32_16x16x32_bf16 v[20:23], v[222:225], v[184:187], v[20:23]
	v_mfma_f32_16x16x32_bf16 v[16:19], v[230:233], v[184:187], v[16:19]
	v_mfma_f32_16x16x32_bf16 v[12:15], v[222:225], v[192:195], v[12:15]
	v_mfma_f32_16x16x32_bf16 v[8:11], v[230:233], v[192:195], v[8:11]
	v_mfma_f32_16x16x32_bf16 v[4:7], v[222:225], v[200:203], v[4:7]
	v_mfma_f32_16x16x32_bf16 v[0:3], v[230:233], v[200:203], v[0:3]
	s_add_i32 s15, s15, 2
	s_add_u32 s12, s12, 0x100
	s_addc_u32 s13, s13, 0
	s_cmp_lt_u32 s15, 60
	s_barrier
	s_cbranch_scc1 .LBB0_52
	s_add_u32 s10, s10, 0x101f80
	s_addc_u32 s11, s11, 0
	v_lshl_add_u64 v[134:135], s[10:11], 0, v[134:135]
	s_mov_b32 m0, s35
	v_lshl_add_u64 v[130:131], v[130:131], 1, v[134:135]
	ds_read_b128 v[138:141], v152
	ds_read_b128 v[142:145], v152 offset:1024
	ds_read_b128 v[156:159], v152 offset:2048
	ds_read_b128 v[160:163], v152 offset:3072
	ds_read_b128 v[164:167], v147
	ds_read_b128 v[168:171], v147 offset:1024
	ds_read_b128 v[172:175], v153
	ds_read_b128 v[176:179], v153 offset:1024
	ds_read_b128 v[180:183], v154
	ds_read_b128 v[184:187], v154 offset:1024
	ds_read_b128 v[188:191], v155
	ds_read_b128 v[192:195], v155 offset:1024
	global_load_lds_dwordx4 v[130:131], off
	v_lshl_add_u64 v[130:131], s[10:11], 0, v[136:137]
	v_lshl_add_u64 v[130:131], v[132:133], 1, v[130:131]
	s_mov_b32 m0, s14
	s_nop 0
	global_load_lds_dwordx4 v[130:131], off
	s_barrier
	s_waitcnt lgkmcnt(0)
	s_waitcnt lgkmcnt(0)
	v_mfma_f32_16x16x32_bf16 v[126:129], v[138:141], v[164:167], v[126:129]
	v_mfma_f32_16x16x32_bf16 v[122:125], v[156:159], v[164:167], v[122:125]
	v_mfma_f32_16x16x32_bf16 v[118:121], v[138:141], v[172:175], v[118:121]
	v_mfma_f32_16x16x32_bf16 v[114:117], v[156:159], v[172:175], v[114:117]
	v_mfma_f32_16x16x32_bf16 v[110:113], v[138:141], v[180:183], v[110:113]
	v_mfma_f32_16x16x32_bf16 v[106:109], v[156:159], v[180:183], v[106:109]
	v_mfma_f32_16x16x32_bf16 v[102:105], v[138:141], v[188:191], v[102:105]
	v_mfma_f32_16x16x32_bf16 v[98:101], v[156:159], v[188:191], v[98:101]
	v_mfma_f32_16x16x32_bf16 v[126:129], v[142:145], v[168:171], v[126:129]
	v_mfma_f32_16x16x32_bf16 v[122:125], v[160:163], v[168:171], v[122:125]
	v_mfma_f32_16x16x32_bf16 v[118:121], v[142:145], v[176:179], v[118:121]
	v_mfma_f32_16x16x32_bf16 v[114:117], v[160:163], v[176:179], v[114:117]
	v_mfma_f32_16x16x32_bf16 v[110:113], v[142:145], v[184:187], v[110:113]
	v_mfma_f32_16x16x32_bf16 v[106:109], v[160:163], v[184:187], v[106:109]
	v_mfma_f32_16x16x32_bf16 v[102:105], v[142:145], v[192:195], v[102:105]
	v_mfma_f32_16x16x32_bf16 v[98:101], v[160:163], v[192:195], v[98:101]
	s_barrier
	ds_read_b128 v[130:133], v150
	ds_read_b128 v[134:137], v150 offset:1024
	ds_read_b128 v[196:199], v150 offset:2048
	ds_read_b128 v[200:203], v150 offset:3072
	s_barrier
	s_waitcnt lgkmcnt(0)
	s_waitcnt lgkmcnt(0)
	v_mfma_f32_16x16x32_bf16 v[90:93], v[196:199], v[164:167], v[90:93]
	v_mfma_f32_16x16x32_bf16 v[86:89], v[130:133], v[172:175], v[86:89]
	v_mfma_f32_16x16x32_bf16 v[82:85], v[196:199], v[172:175], v[82:85]
	v_mfma_f32_16x16x32_bf16 v[78:81], v[130:133], v[180:183], v[78:81]
	v_mfma_f32_16x16x32_bf16 v[74:77], v[196:199], v[180:183], v[74:77]
	v_mfma_f32_16x16x32_bf16 v[70:73], v[130:133], v[188:191], v[70:73]
	v_mfma_f32_16x16x32_bf16 v[66:69], v[196:199], v[188:191], v[66:69]
	v_mfma_f32_16x16x32_bf16 v[94:97], v[130:133], v[164:167], v[94:97]
	v_mfma_f32_16x16x32_bf16 v[90:93], v[200:203], v[168:171], v[90:93]
	v_mfma_f32_16x16x32_bf16 v[86:89], v[134:137], v[176:179], v[86:89]
	v_mfma_f32_16x16x32_bf16 v[82:85], v[200:203], v[176:179], v[82:85]
	v_mfma_f32_16x16x32_bf16 v[78:81], v[134:137], v[184:187], v[78:81]
	v_mfma_f32_16x16x32_bf16 v[74:77], v[200:203], v[184:187], v[74:77]
	v_mfma_f32_16x16x32_bf16 v[70:73], v[134:137], v[192:195], v[70:73]
	v_mfma_f32_16x16x32_bf16 v[66:69], v[200:203], v[192:195], v[66:69]
	v_mfma_f32_16x16x32_bf16 v[218:221], v[134:137], v[168:171], v[94:97]
	s_barrier
;   #define LDA(dst,b,h) _Pragma("unroll") for(int m=0;m<4;++m) _Pragma("unroll") for(int k=0;k<2;++k) \
;     dst[m][k]=*reinterpret_cast<const s16x8*>((char*)SA(b,h)+lds_byte8(wr*64+m*16+fr,k*32+fq*8))
;   #define LDB(dst,b,h) _Pragma("unroll") for(int n=0;n<2;++n) _Pragma("unroll") for(int k=0;k<2;++k) \
;     dst[n][k]=*reinterpret_cast<const s16x8*>((char*)SB(b,h)+lds_byte8(wc*32+n*16+fr,k*32+fq*8))
;   #define MMA(ai,bj,At,Bt) do{__builtin_amdgcn_s_setprio(1); \
;     _Pragma("unroll") for(int m=0;m<4;++m) _Pragma("unroll") for(int n=0;n<2;++n) _Pragma("unroll") for(int k=0;k<2;++k) \
;       acc[ai][bj][m][n]=__builtin_amdgcn_mfma_f32_16x16x32_bf16(Bt[n][k],At[m][k],acc[ai][bj][m][n],0,0,0); \
;     __builtin_amdgcn_s_setprio(0);}while(0)
;   #define WAIT_V(n) asm volatile("s_waitcnt vmcnt(" #n ")":::"memory")
;   #define WAIT_L(n) asm volatile("s_waitcnt lgkmcnt(" #n ")":::"memory")
;   #define BAR __builtin_amdgcn_s_barrier()
; template <class Epi>
; __device__ __forceinline__ void gemm_tile8(const u16* __restrict__ A, long lda, const u16* __restrict__ Bt, long ldb, int K, char* shmc, Epi epi){
;     ...
;     LDA(At,0,1); WAIT_V(4); BAR; WAIT_L(0); MMA(1,0,At,B0); MMA(1,1,At,B1); BAR; }
;   { LDB(B0,1,0); LDA(At,1,0); WAIT_V(2); BAR; WAIT_L(0); MMA(0,0,At,B0); BAR;
;     LDB(B1,1,1); WAIT_V(0); BAR; WAIT_L(0); MMA(0,1,At,B1); BAR;
	s_nop 0
	ds_read_b128 v[94:97], v147 offset:16384
	ds_read_b128 v[164:167], v147 offset:17408
	ds_read_b128 v[168:171], v153 offset:16384
	ds_read_b128 v[172:175], v153 offset:17408
	ds_read_b128 v[176:179], v154 offset:16384
	ds_read_b128 v[180:183], v154 offset:17408
	ds_read_b128 v[184:187], v155 offset:16384
	ds_read_b128 v[188:191], v155 offset:17408
	s_waitcnt vmcnt(4)
	s_barrier
	s_waitcnt lgkmcnt(0)
	s_waitcnt lgkmcnt(0)
	v_mfma_f32_16x16x32_bf16 v[58:61], v[156:159], v[94:97], v[58:61]
	v_mfma_f32_16x16x32_bf16 v[54:57], v[138:141], v[168:171], v[54:57]
	v_mfma_f32_16x16x32_bf16 v[50:53], v[156:159], v[168:171], v[50:53]
	v_mfma_f32_16x16x32_bf16 v[46:49], v[138:141], v[176:179], v[46:49]
	v_mfma_f32_16x16x32_bf16 v[42:45], v[156:159], v[176:179], v[42:45]
	v_mfma_f32_16x16x32_bf16 v[38:41], v[138:141], v[184:187], v[38:41]
	v_mfma_f32_16x16x32_bf16 v[34:37], v[156:159], v[184:187], v[34:37]
	v_mfma_f32_16x16x32_bf16 v[62:65], v[138:141], v[94:97], v[62:65]
	v_mfma_f32_16x16x32_bf16 v[58:61], v[160:163], v[164:167], v[58:61]
	v_mfma_f32_16x16x32_bf16 v[54:57], v[142:145], v[172:175], v[54:57]
	v_mfma_f32_16x16x32_bf16 v[50:53], v[160:163], v[172:175], v[50:53]
	v_mfma_f32_16x16x32_bf16 v[46:49], v[142:145], v[180:183], v[46:49]
	v_mfma_f32_16x16x32_bf16 v[42:45], v[160:163], v[180:183], v[42:45]
	v_mfma_f32_16x16x32_bf16 v[38:41], v[142:145], v[188:191], v[38:41]
	v_mfma_f32_16x16x32_bf16 v[34:37], v[160:163], v[188:191], v[34:37]
	v_mfma_f32_16x16x32_bf16 v[192:195], v[142:145], v[164:167], v[62:65]
	v_mfma_f32_16x16x32_bf16 v[28:31], v[130:133], v[94:97], v[28:31]
	v_mfma_f32_16x16x32_bf16 v[24:27], v[196:199], v[94:97], v[24:27]
	v_mfma_f32_16x16x32_bf16 v[20:23], v[130:133], v[168:171], v[20:23]
	v_mfma_f32_16x16x32_bf16 v[16:19], v[196:199], v[168:171], v[16:19]
	v_mfma_f32_16x16x32_bf16 v[12:15], v[130:133], v[176:179], v[12:15]
	v_mfma_f32_16x16x32_bf16 v[8:11], v[196:199], v[176:179], v[8:11]
	v_mfma_f32_16x16x32_bf16 v[4:7], v[130:133], v[184:187], v[4:7]
	v_mfma_f32_16x16x32_bf16 v[0:3], v[196:199], v[184:187], v[0:3]
	v_mfma_f32_16x16x32_bf16 v[28:31], v[134:137], v[164:167], v[28:31]
	v_mfma_f32_16x16x32_bf16 v[24:27], v[200:203], v[164:167], v[24:27]
	v_mfma_f32_16x16x32_bf16 v[20:23], v[134:137], v[172:175], v[20:23]
	v_mfma_f32_16x16x32_bf16 v[16:19], v[200:203], v[172:175], v[16:19]
	v_mfma_f32_16x16x32_bf16 v[12:15], v[134:137], v[180:183], v[12:15]
	v_mfma_f32_16x16x32_bf16 v[8:11], v[200:203], v[180:183], v[8:11]
	v_mfma_f32_16x16x32_bf16 v[4:7], v[134:137], v[188:191], v[4:7]
	v_mfma_f32_16x16x32_bf16 v[0:3], v[200:203], v[188:191], v[0:3]
	s_barrier
	ds_read_b128 v[130:133], v149
	ds_read_b128 v[134:137], v149 offset:1024
	ds_read_b128 v[138:141], v149 offset:2048
	ds_read_b128 v[142:145], v149 offset:3072
	ds_read_b128 v[62:65], v147 offset:32768
	ds_read_b128 v[156:159], v147 offset:33792
	ds_read_b128 v[160:163], v153 offset:32768
	ds_read_b128 v[164:167], v153 offset:33792
	ds_read_b128 v[168:171], v154 offset:32768
	ds_read_b128 v[172:175], v154 offset:33792
	ds_read_b128 v[176:179], v155 offset:32768
	ds_read_b128 v[180:183], v155 offset:33792
	s_waitcnt vmcnt(2)
	s_barrier
	s_waitcnt lgkmcnt(0)
	s_waitcnt lgkmcnt(0)
	v_mfma_f32_16x16x32_bf16 v[94:97], v[130:133], v[62:65], v[126:129]
	v_mfma_f32_16x16x32_bf16 v[126:129], v[134:137], v[156:159], v[94:97]
	v_mfma_f32_16x16x32_bf16 v[94:97], v[138:141], v[62:65], v[122:125]
	v_mfma_f32_16x16x32_bf16 v[122:125], v[142:145], v[156:159], v[94:97]
	v_mfma_f32_16x16x32_bf16 v[94:97], v[130:133], v[160:163], v[118:121]
	v_mfma_f32_16x16x32_bf16 v[118:121], v[134:137], v[164:167], v[94:97]
	v_mfma_f32_16x16x32_bf16 v[94:97], v[138:141], v[160:163], v[114:117]
	v_mfma_f32_16x16x32_bf16 v[114:117], v[142:145], v[164:167], v[94:97]
	v_mfma_f32_16x16x32_bf16 v[94:97], v[130:133], v[168:171], v[110:113]
	v_mfma_f32_16x16x32_bf16 v[110:113], v[134:137], v[172:175], v[94:97]
	v_mfma_f32_16x16x32_bf16 v[94:97], v[138:141], v[168:171], v[106:109]
	v_mfma_f32_16x16x32_bf16 v[106:109], v[142:145], v[172:175], v[94:97]
	v_mfma_f32_16x16x32_bf16 v[94:97], v[130:133], v[176:179], v[102:105]
	v_mfma_f32_16x16x32_bf16 v[102:105], v[134:137], v[180:183], v[94:97]
	v_mfma_f32_16x16x32_bf16 v[94:97], v[138:141], v[176:179], v[98:101]
	v_mfma_f32_16x16x32_bf16 v[94:97], v[142:145], v[180:183], v[94:97]
	s_barrier
;   #define LDA(dst,b,h) _Pragma("unroll") for(int m=0;m<4;++m) _Pragma("unroll") for(int k=0;k<2;++k) \
;     dst[m][k]=*reinterpret_cast<const s16x8*>((char*)SA(b,h)+lds_byte8(wr*64+m*16+fr,k*32+fq*8))
;   #define LDB(dst,b,h) _Pragma("unroll") for(int n=0;n<2;++n) _Pragma("unroll") for(int k=0;k<2;++k) \
;     dst[n][k]=*reinterpret_cast<const s16x8*>((char*)SB(b,h)+lds_byte8(wc*32+n*16+fr,k*32+fq*8))
;   #define MMA(ai,bj,At,Bt) do{__builtin_amdgcn_s_setprio(1); \
;     _Pragma("unroll") for(int m=0;m<4;++m) _Pragma("unroll") for(int n=0;n<2;++n) _Pragma("unroll") for(int k=0;k<2;++k) \
;       acc[ai][bj][m][n]=__builtin_amdgcn_mfma_f32_16x16x32_bf16(Bt[n][k],At[m][k],acc[ai][bj][m][n],0,0,0); \
;     __builtin_amdgcn_s_setprio(0);}while(0)
;   #define WAIT_V(n) asm volatile("s_waitcnt vmcnt(" #n ")":::"memory")
;   #define WAIT_L(n) asm volatile("s_waitcnt lgkmcnt(" #n ")":::"memory")
;   #define BAR __builtin_amdgcn_s_barrier()
; template <class Epi>
; __device__ __forceinline__ void gemm_tile8(const u16* __restrict__ A, long lda, const u16* __restrict__ Bt, long ldb, int K, char* shmc, Epi epi){
;     ...
;   { LDB(B0,1,0); LDA(At,1,0); WAIT_V(2); BAR; WAIT_L(0); MMA(0,0,At,B0); BAR;
;     LDB(B1,1,1); WAIT_V(0); BAR; WAIT_L(0); MMA(0,1,At,B1); BAR;
;     LDA(At,1,1); BAR; WAIT_L(0); MMA(1,0,At,B0); MMA(1,1,At,B1); BAR; }
;   if(wr==0)BAR;
	ds_read_b128 v[184:187], v148
	ds_read_b128 v[188:191], v148 offset:1024
	ds_read_b128 v[196:199], v148 offset:2048
	ds_read_b128 v[148:151], v148 offset:3072
	s_waitcnt vmcnt(0)
	s_barrier
	s_waitcnt lgkmcnt(0)
	s_waitcnt lgkmcnt(0)
	v_mfma_f32_16x16x32_bf16 v[98:101], v[184:187], v[62:65], v[218:221]
	v_mfma_f32_16x16x32_bf16 v[62:65], v[196:199], v[62:65], v[90:93]
	v_mfma_f32_16x16x32_bf16 v[90:93], v[148:151], v[156:159], v[62:65]
	v_mfma_f32_16x16x32_bf16 v[62:65], v[184:187], v[160:163], v[86:89]
	v_mfma_f32_16x16x32_bf16 v[86:89], v[188:191], v[164:167], v[62:65]
	v_mfma_f32_16x16x32_bf16 v[62:65], v[196:199], v[160:163], v[82:85]
	v_mfma_f32_16x16x32_bf16 v[82:85], v[148:151], v[164:167], v[62:65]
	v_mfma_f32_16x16x32_bf16 v[62:65], v[184:187], v[168:171], v[78:81]
	v_mfma_f32_16x16x32_bf16 v[78:81], v[188:191], v[172:175], v[62:65]
	v_mfma_f32_16x16x32_bf16 v[62:65], v[196:199], v[168:171], v[74:77]
	v_mfma_f32_16x16x32_bf16 v[74:77], v[148:151], v[172:175], v[62:65]
	v_mfma_f32_16x16x32_bf16 v[62:65], v[184:187], v[176:179], v[70:73]
	v_mfma_f32_16x16x32_bf16 v[70:73], v[188:191], v[180:183], v[62:65]
	v_mfma_f32_16x16x32_bf16 v[62:65], v[196:199], v[176:179], v[66:69]
	v_mfma_f32_16x16x32_bf16 v[98:101], v[188:191], v[156:159], v[98:101]
	v_mfma_f32_16x16x32_bf16 v[62:65], v[148:151], v[180:183], v[62:65]
	s_barrier
	ds_read_b128 v[156:159], v147 offset:49152
	ds_read_b128 v[160:163], v147 offset:50176
	ds_read_b128 v[164:167], v153 offset:49152
	ds_read_b128 v[168:171], v153 offset:50176
	ds_read_b128 v[172:175], v154 offset:49152
	ds_read_b128 v[176:179], v154 offset:50176
	ds_read_b128 v[180:183], v155 offset:49152
	ds_read_b128 v[152:155], v155 offset:50176
	s_barrier
	s_waitcnt lgkmcnt(0)
	s_waitcnt lgkmcnt(0)
	v_mfma_f32_16x16x32_bf16 v[66:69], v[130:133], v[156:159], v[192:195]
	v_mfma_f32_16x16x32_bf16 v[58:61], v[138:141], v[156:159], v[58:61]
	v_mfma_f32_16x16x32_bf16 v[54:57], v[130:133], v[164:167], v[54:57]
	v_mfma_f32_16x16x32_bf16 v[50:53], v[138:141], v[164:167], v[50:53]
	v_mfma_f32_16x16x32_bf16 v[46:49], v[130:133], v[172:175], v[46:49]
	v_mfma_f32_16x16x32_bf16 v[42:45], v[138:141], v[172:175], v[42:45]
	v_mfma_f32_16x16x32_bf16 v[38:41], v[130:133], v[180:183], v[38:41]
	v_mfma_f32_16x16x32_bf16 v[34:37], v[138:141], v[180:183], v[34:37]
	v_mfma_f32_16x16x32_bf16 v[66:69], v[134:137], v[160:163], v[66:69]
	v_mfma_f32_16x16x32_bf16 v[58:61], v[142:145], v[160:163], v[58:61]
	v_mfma_f32_16x16x32_bf16 v[54:57], v[134:137], v[168:171], v[54:57]
	v_mfma_f32_16x16x32_bf16 v[50:53], v[142:145], v[168:171], v[50:53]
	v_mfma_f32_16x16x32_bf16 v[46:49], v[134:137], v[176:179], v[46:49]
	v_mfma_f32_16x16x32_bf16 v[42:45], v[142:145], v[176:179], v[42:45]
	v_mfma_f32_16x16x32_bf16 v[38:41], v[134:137], v[152:155], v[38:41]
	v_mfma_f32_16x16x32_bf16 v[34:37], v[142:145], v[152:155], v[34:37]
	v_mfma_f32_16x16x32_bf16 v[28:31], v[184:187], v[156:159], v[28:31]
	v_mfma_f32_16x16x32_bf16 v[24:27], v[196:199], v[156:159], v[24:27]
	v_mfma_f32_16x16x32_bf16 v[20:23], v[184:187], v[164:167], v[20:23]
	v_mfma_f32_16x16x32_bf16 v[16:19], v[196:199], v[164:167], v[16:19]
	v_mfma_f32_16x16x32_bf16 v[12:15], v[184:187], v[172:175], v[12:15]
	v_mfma_f32_16x16x32_bf16 v[8:11], v[196:199], v[172:175], v[8:11]
	v_mfma_f32_16x16x32_bf16 v[4:7], v[184:187], v[180:183], v[4:7]
	v_mfma_f32_16x16x32_bf16 v[0:3], v[196:199], v[180:183], v[0:3]
	v_mfma_f32_16x16x32_bf16 v[28:31], v[188:191], v[160:163], v[28:31]
	v_mfma_f32_16x16x32_bf16 v[24:27], v[148:151], v[160:163], v[24:27]
	v_mfma_f32_16x16x32_bf16 v[20:23], v[188:191], v[168:171], v[20:23]
	v_mfma_f32_16x16x32_bf16 v[16:19], v[148:151], v[168:171], v[16:19]
	v_mfma_f32_16x16x32_bf16 v[12:15], v[188:191], v[176:179], v[12:15]
	v_mfma_f32_16x16x32_bf16 v[8:11], v[148:151], v[176:179], v[8:11]
	v_mfma_f32_16x16x32_bf16 v[4:7], v[188:191], v[152:155], v[4:7]
	v_mfma_f32_16x16x32_bf16 v[0:3], v[148:151], v[152:155], v[0:3]
	s_cmpk_gt_u32 s7, 0xff
	s_barrier
	s_cbranch_scc1 .LBB0_46
	s_barrier
	s_branch .LBB0_46

;   #define STAGE(P,BASE,LD,br,kt) do{long _g=(long)(br)*LD+(long)(kt)*BK; \
;     _Pragma("unroll") for(int _i=0;_i<2;++_i){ \
;       __builtin_amdgcn_global_load_lds((const unsigned*)(BASE+_g+(long)sR[_i]*LD+sC[_i]), \
;         LDSP(unsigned,(char*)(P)+wid*1024+_i*8192),16,0,0);}}while(0)
;   #define LDA(dst,b,h) _Pragma("unroll") for(int m=0;m<4;++m) _Pragma("unroll") for(int k=0;k<2;++k) \
;     dst[m][k]=*reinterpret_cast<const s16x8*>((char*)SA(b,h)+lds_byte8(wr*64+m*16+fr,k*32+fq*8))
;   #define LDB(dst,b,h) _Pragma("unroll") for(int n=0;n<2;++n) _Pragma("unroll") for(int k=0;k<2;++k) \
;     dst[n][k]=*reinterpret_cast<const s16x8*>((char*)SB(b,h)+lds_byte8(wc*32+n*16+fr,k*32+fq*8))
;   #define MMA(ai,bj,At,Bt) do{__builtin_amdgcn_s_setprio(1); \
;     _Pragma("unroll") for(int m=0;m<4;++m) _Pragma("unroll") for(int n=0;n<2;++n) _Pragma("unroll") for(int k=0;k<2;++k) \
;       acc[ai][bj][m][n]=__builtin_amdgcn_mfma_f32_16x16x32_bf16(Bt[n][k],At[m][k],acc[ai][bj][m][n],0,0,0); \
;     __builtin_amdgcn_s_setprio(0);}while(0)
;   #define WAIT_V(n) asm volatile("s_waitcnt vmcnt(" #n ")":::"memory")
;   #define WAIT_L(n) asm volatile("s_waitcnt lgkmcnt(" #n ")":::"memory")
;   #define BAR __builtin_amdgcn_s_barrier()
;   #define SCHED __builtin_amdgcn_sched_barrier(0)
; template <class Epi>
; __device__ __forceinline__ void gemm_tile8(const u16* __restrict__ A, long lda, const u16* __restrict__ Bt, long ldb, int K, char* shmc, Epi epi){
;     ...
;   for(int t=0;t<nt-2;t+=2){
;     LDB(B0,0,0); SCHED; LDA(At,0,0); STAGE(SA(1,1),A,lda,brow+HALF,t+1);
;     WAIT_L(8); BAR; WAIT_L(0); MMA(0,0,At,B0); BAR; SCHED;
;     LDB(B1,0,1); STAGE(SB(0,0),Bt,ldb,bcol,t+2);
;     BAR; WAIT_L(0); MMA(0,1,At,B1); BAR;
;     LDA(At,0,1); STAGE(SA(0,0),A,lda,brow,t+2);
;     BAR; WAIT_L(0); MMA(1,0,At,B0); BAR; SCHED;
;     STAGE(SB(0,1),Bt,ldb,bcol+HALF,t+2);
;     WAIT_V(6); BAR; MMA(1,1,At,B1); BAR;
.LBB0_963:
	ds_read_b128 v[156:159], v152
	ds_read_b128 v[160:163], v152 offset:1024
	ds_read_b128 v[164:167], v152 offset:2048
	ds_read_b128 v[168:171], v152 offset:3072
	v_lshl_add_u64 v[234:235], v[142:143], 0, s[10:11]
	s_add_i32 s31, s16, 0xc000
	v_add_u32_e32 v153, s28, v151
	v_add_u32_e32 v154, s29, v151
	v_add_u32_e32 v155, s30, v151
	v_lshl_add_u64 v[218:219], v[234:235], 0, s[34:35]
	s_mov_b32 m0, s31
	v_lshl_add_u64 v[236:237], v[144:145], 0, s[10:11]
	s_add_i32 s13, s16, 0xe000
	ds_read_b128 v[172:175], v147
	ds_read_b128 v[176:179], v147 offset:1024
	ds_read_b128 v[180:183], v153
	ds_read_b128 v[184:187], v153 offset:1024
	ds_read_b128 v[188:191], v154
	ds_read_b128 v[192:195], v154 offset:1024
	ds_read_b128 v[196:199], v155
	ds_read_b128 v[200:203], v155 offset:1024
	global_load_lds_dwordx4 v[218:219], off
	v_lshl_add_u64 v[218:219], v[236:237], 0, s[34:35]
	s_mov_b32 m0, s13
	s_nop 0
	global_load_lds_dwordx4 v[218:219], off
	s_waitcnt lgkmcnt(8)
	s_barrier
	s_waitcnt lgkmcnt(0)
	s_waitcnt lgkmcnt(0)
	v_mfma_f32_16x16x32_bf16 v[126:129], v[156:159], v[172:175], v[126:129]
	v_mfma_f32_16x16x32_bf16 v[122:125], v[164:167], v[172:175], v[122:125]
	v_mfma_f32_16x16x32_bf16 v[118:121], v[156:159], v[180:183], v[118:121]
	v_mfma_f32_16x16x32_bf16 v[114:117], v[164:167], v[180:183], v[114:117]
	v_mfma_f32_16x16x32_bf16 v[110:113], v[156:159], v[188:191], v[110:113]
	v_mfma_f32_16x16x32_bf16 v[106:109], v[164:167], v[188:191], v[106:109]
	v_mfma_f32_16x16x32_bf16 v[102:105], v[156:159], v[196:199], v[102:105]
	v_mfma_f32_16x16x32_bf16 v[98:101], v[164:167], v[196:199], v[98:101]
	v_mfma_f32_16x16x32_bf16 v[126:129], v[160:163], v[176:179], v[126:129]
	v_mfma_f32_16x16x32_bf16 v[122:125], v[168:171], v[176:179], v[122:125]
	v_mfma_f32_16x16x32_bf16 v[118:121], v[160:163], v[184:187], v[118:121]
	v_mfma_f32_16x16x32_bf16 v[114:117], v[168:171], v[184:187], v[114:117]
	v_mfma_f32_16x16x32_bf16 v[110:113], v[160:163], v[192:195], v[110:113]
	v_mfma_f32_16x16x32_bf16 v[106:109], v[168:171], v[192:195], v[106:109]
	v_mfma_f32_16x16x32_bf16 v[102:105], v[160:163], v[200:203], v[102:105]
	v_mfma_f32_16x16x32_bf16 v[98:101], v[168:171], v[200:203], v[98:101]
	s_barrier
	v_lshl_add_u64 v[238:239], v[138:139], 0, s[10:11]
	s_mov_b32 m0, s17
	v_lshl_add_u64 v[240:241], v[238:239], 0, s[36:37]
	ds_read_b128 v[218:221], v150
	ds_read_b128 v[222:225], v150 offset:1024
	ds_read_b128 v[226:229], v150 offset:2048
	ds_read_b128 v[230:233], v150 offset:3072
	global_load_lds_dwordx4 v[240:241], off
	v_lshl_add_u64 v[240:241], v[140:141], 0, s[10:11]
	v_lshl_add_u64 v[242:243], v[240:241], 0, s[36:37]
	s_mov_b32 m0, s18
	s_nop 0
	global_load_lds_dwordx4 v[242:243], off
	s_barrier
	s_waitcnt lgkmcnt(0)
	s_waitcnt lgkmcnt(0)
	v_mfma_f32_16x16x32_bf16 v[94:97], v[218:221], v[172:175], v[94:97]
	v_mfma_f32_16x16x32_bf16 v[90:93], v[226:229], v[172:175], v[90:93]
	v_mfma_f32_16x16x32_bf16 v[86:89], v[218:221], v[180:183], v[86:89]
	v_mfma_f32_16x16x32_bf16 v[82:85], v[226:229], v[180:183], v[82:85]
	v_mfma_f32_16x16x32_bf16 v[78:81], v[218:221], v[188:191], v[78:81]
	v_mfma_f32_16x16x32_bf16 v[74:77], v[226:229], v[188:191], v[74:77]
	v_mfma_f32_16x16x32_bf16 v[70:73], v[218:221], v[196:199], v[70:73]
	v_mfma_f32_16x16x32_bf16 v[66:69], v[226:229], v[196:199], v[66:69]
	v_mfma_f32_16x16x32_bf16 v[94:97], v[222:225], v[176:179], v[94:97]
	v_mfma_f32_16x16x32_bf16 v[90:93], v[230:233], v[176:179], v[90:93]
	v_mfma_f32_16x16x32_bf16 v[86:89], v[222:225], v[184:187], v[86:89]
	v_mfma_f32_16x16x32_bf16 v[82:85], v[230:233], v[184:187], v[82:85]
	v_mfma_f32_16x16x32_bf16 v[78:81], v[222:225], v[192:195], v[78:81]
	v_mfma_f32_16x16x32_bf16 v[74:77], v[230:233], v[192:195], v[74:77]
	v_mfma_f32_16x16x32_bf16 v[70:73], v[222:225], v[200:203], v[70:73]
	v_mfma_f32_16x16x32_bf16 v[66:69], v[230:233], v[200:203], v[66:69]
	s_mov_b32 m0, s16
	v_lshl_add_u64 v[242:243], v[234:235], 0, s[36:37]
	s_barrier
	ds_read_b128 v[172:175], v147 offset:16384
	ds_read_b128 v[176:179], v147 offset:17408
	ds_read_b128 v[180:183], v153 offset:16384
	ds_read_b128 v[184:187], v153 offset:17408
	ds_read_b128 v[188:191], v154 offset:16384
	ds_read_b128 v[192:195], v154 offset:17408
	ds_read_b128 v[196:199], v155 offset:16384
	ds_read_b128 v[200:203], v155 offset:17408
	global_load_lds_dwordx4 v[242:243], off
	v_lshl_add_u64 v[242:243], v[236:237], 0, s[36:37]
	s_mov_b32 m0, s19
	s_nop 0
	global_load_lds_dwordx4 v[242:243], off
	s_barrier
	s_waitcnt lgkmcnt(0)
	s_waitcnt lgkmcnt(0)
	v_mfma_f32_16x16x32_bf16 v[62:65], v[156:159], v[172:175], v[62:65]
	v_mfma_f32_16x16x32_bf16 v[58:61], v[164:167], v[172:175], v[58:61]
	v_mfma_f32_16x16x32_bf16 v[54:57], v[156:159], v[180:183], v[54:57]
	v_mfma_f32_16x16x32_bf16 v[50:53], v[164:167], v[180:183], v[50:53]
	v_mfma_f32_16x16x32_bf16 v[46:49], v[156:159], v[188:191], v[46:49]
	v_mfma_f32_16x16x32_bf16 v[42:45], v[164:167], v[188:191], v[42:45]
	v_mfma_f32_16x16x32_bf16 v[38:41], v[156:159], v[196:199], v[38:41]
	v_mfma_f32_16x16x32_bf16 v[34:37], v[164:167], v[196:199], v[34:37]
	v_mfma_f32_16x16x32_bf16 v[62:65], v[160:163], v[176:179], v[62:65]
	v_mfma_f32_16x16x32_bf16 v[58:61], v[168:171], v[176:179], v[58:61]
	v_mfma_f32_16x16x32_bf16 v[54:57], v[160:163], v[184:187], v[54:57]
	v_mfma_f32_16x16x32_bf16 v[50:53], v[168:171], v[184:187], v[50:53]
	v_mfma_f32_16x16x32_bf16 v[46:49], v[160:163], v[192:195], v[46:49]
	v_mfma_f32_16x16x32_bf16 v[42:45], v[168:171], v[192:195], v[42:45]
	v_mfma_f32_16x16x32_bf16 v[38:41], v[160:163], v[200:203], v[38:41]
	v_mfma_f32_16x16x32_bf16 v[34:37], v[168:171], v[200:203], v[34:37]
	s_barrier
;   #define STAGE(P,BASE,LD,br,kt) do{long _g=(long)(br)*LD+(long)(kt)*BK; \
;     _Pragma("unroll") for(int _i=0;_i<2;++_i){ \
;       __builtin_amdgcn_global_load_lds((const unsigned*)(BASE+_g+(long)sR[_i]*LD+sC[_i]), \
;         LDSP(unsigned,(char*)(P)+wid*1024+_i*8192),16,0,0);}}while(0)
;   #define LDA(dst,b,h) _Pragma("unroll") for(int m=0;m<4;++m) _Pragma("unroll") for(int k=0;k<2;++k) \
;     dst[m][k]=*reinterpret_cast<const s16x8*>((char*)SA(b,h)+lds_byte8(wr*64+m*16+fr,k*32+fq*8))
;   #define LDB(dst,b,h) _Pragma("unroll") for(int n=0;n<2;++n) _Pragma("unroll") for(int k=0;k<2;++k) \
;     dst[n][k]=*reinterpret_cast<const s16x8*>((char*)SB(b,h)+lds_byte8(wc*32+n*16+fr,k*32+fq*8))
;   #define MMA(ai,bj,At,Bt) do{__builtin_amdgcn_s_setprio(1); \
;     _Pragma("unroll") for(int m=0;m<4;++m) _Pragma("unroll") for(int n=0;n<2;++n) _Pragma("unroll") for(int k=0;k<2;++k) \
;       acc[ai][bj][m][n]=__builtin_amdgcn_mfma_f32_16x16x32_bf16(Bt[n][k],At[m][k],acc[ai][bj][m][n],0,0,0); \
;     __builtin_amdgcn_s_setprio(0);}while(0)
;   #define WAIT_V(n) asm volatile("s_waitcnt vmcnt(" #n ")":::"memory")
;   #define WAIT_L(n) asm volatile("s_waitcnt lgkmcnt(" #n ")":::"memory")
;   #define BAR __builtin_amdgcn_s_barrier()
;   #define SCHED __builtin_amdgcn_sched_barrier(0)
; template <class Epi>
; __device__ __forceinline__ void gemm_tile8(const u16* __restrict__ A, long lda, const u16* __restrict__ Bt, long ldb, int K, char* shmc, Epi epi){
;     ...
;     STAGE(SB(0,1),Bt,ldb,bcol+HALF,t+2);
;     WAIT_V(6); BAR; MMA(1,1,At,B1); BAR;
;     LDB(B0,1,0); SCHED; LDA(At,1,0); STAGE(SA(0,1),A,lda,brow+HALF,t+2);
;     WAIT_L(8); BAR; WAIT_L(0); MMA(0,0,At,B0); BAR; SCHED;
;     LDB(B1,1,1); STAGE(SB(1,0),Bt,ldb,bcol,t+3);
;     BAR; WAIT_L(0); MMA(0,1,At,B1); BAR;
;     LDA(At,1,1); STAGE(SA(1,0),A,lda,brow,t+3);
;     BAR; WAIT_L(0); MMA(1,0,At,B0); BAR; SCHED;
	s_mov_b32 m0, s20
	v_lshl_add_u64 v[156:157], v[238:239], 0, s[38:39]
	global_load_lds_dwordx4 v[156:157], off
	v_lshl_add_u64 v[156:157], v[240:241], 0, s[38:39]
	s_mov_b32 m0, s21
	s_nop 0
	global_load_lds_dwordx4 v[156:157], off
	s_waitcnt vmcnt(6)
	s_barrier
	v_mfma_f32_16x16x32_bf16 v[28:31], v[218:221], v[172:175], v[28:31]
	v_mfma_f32_16x16x32_bf16 v[24:27], v[226:229], v[172:175], v[24:27]
	v_mfma_f32_16x16x32_bf16 v[20:23], v[218:221], v[180:183], v[20:23]
	v_mfma_f32_16x16x32_bf16 v[16:19], v[226:229], v[180:183], v[16:19]
	v_mfma_f32_16x16x32_bf16 v[12:15], v[218:221], v[188:191], v[12:15]
	v_mfma_f32_16x16x32_bf16 v[8:11], v[226:229], v[188:191], v[8:11]
	v_mfma_f32_16x16x32_bf16 v[4:7], v[218:221], v[196:199], v[4:7]
	v_mfma_f32_16x16x32_bf16 v[0:3], v[226:229], v[196:199], v[0:3]
	v_mfma_f32_16x16x32_bf16 v[28:31], v[222:225], v[176:179], v[28:31]
	v_mfma_f32_16x16x32_bf16 v[24:27], v[230:233], v[176:179], v[24:27]
	v_mfma_f32_16x16x32_bf16 v[20:23], v[222:225], v[184:187], v[20:23]
	v_mfma_f32_16x16x32_bf16 v[16:19], v[230:233], v[184:187], v[16:19]
	v_mfma_f32_16x16x32_bf16 v[12:15], v[222:225], v[192:195], v[12:15]
	v_mfma_f32_16x16x32_bf16 v[8:11], v[230:233], v[192:195], v[8:11]
	v_mfma_f32_16x16x32_bf16 v[4:7], v[222:225], v[200:203], v[4:7]
	v_mfma_f32_16x16x32_bf16 v[0:3], v[230:233], v[200:203], v[0:3]
	s_barrier
	ds_read_b128 v[156:159], v149
	ds_read_b128 v[160:163], v149 offset:1024
	ds_read_b128 v[164:167], v149 offset:2048
	ds_read_b128 v[168:171], v149 offset:3072
	s_mov_b32 m0, s22
	v_lshl_add_u64 v[218:219], v[234:235], 0, s[38:39]
	ds_read_b128 v[172:175], v147 offset:32768
	ds_read_b128 v[176:179], v147 offset:33792
	ds_read_b128 v[180:183], v153 offset:32768
	ds_read_b128 v[184:187], v153 offset:33792
	ds_read_b128 v[188:191], v154 offset:32768
	ds_read_b128 v[192:195], v154 offset:33792
	ds_read_b128 v[196:199], v155 offset:32768
	ds_read_b128 v[200:203], v155 offset:33792
	global_load_lds_dwordx4 v[218:219], off
	v_lshl_add_u64 v[218:219], v[236:237], 0, s[38:39]
	s_mov_b32 m0, s23
	s_nop 0
	global_load_lds_dwordx4 v[218:219], off
	s_waitcnt lgkmcnt(8)
	s_barrier
	s_waitcnt lgkmcnt(0)
	s_waitcnt lgkmcnt(0)
	v_mfma_f32_16x16x32_bf16 v[126:129], v[156:159], v[172:175], v[126:129]
	v_mfma_f32_16x16x32_bf16 v[122:125], v[164:167], v[172:175], v[122:125]
	v_mfma_f32_16x16x32_bf16 v[118:121], v[156:159], v[180:183], v[118:121]
	v_mfma_f32_16x16x32_bf16 v[114:117], v[164:167], v[180:183], v[114:117]
	v_mfma_f32_16x16x32_bf16 v[110:113], v[156:159], v[188:191], v[110:113]
	v_mfma_f32_16x16x32_bf16 v[106:109], v[164:167], v[188:191], v[106:109]
	v_mfma_f32_16x16x32_bf16 v[102:105], v[156:159], v[196:199], v[102:105]
	v_mfma_f32_16x16x32_bf16 v[98:101], v[164:167], v[196:199], v[98:101]
	v_mfma_f32_16x16x32_bf16 v[126:129], v[160:163], v[176:179], v[126:129]
	v_mfma_f32_16x16x32_bf16 v[122:125], v[168:171], v[176:179], v[122:125]
	v_mfma_f32_16x16x32_bf16 v[118:121], v[160:163], v[184:187], v[118:121]
	v_mfma_f32_16x16x32_bf16 v[114:117], v[168:171], v[184:187], v[114:117]
	v_mfma_f32_16x16x32_bf16 v[110:113], v[160:163], v[192:195], v[110:113]
	v_mfma_f32_16x16x32_bf16 v[106:109], v[168:171], v[192:195], v[106:109]
	v_mfma_f32_16x16x32_bf16 v[102:105], v[160:163], v[200:203], v[102:105]
	v_mfma_f32_16x16x32_bf16 v[98:101], v[168:171], v[200:203], v[98:101]
	s_barrier
	s_mov_b32 m0, s24
	v_lshl_add_u64 v[242:243], v[238:239], 0, s[40:41]
	ds_read_b128 v[218:221], v148
	ds_read_b128 v[222:225], v148 offset:1024
	ds_read_b128 v[226:229], v148 offset:2048
	ds_read_b128 v[230:233], v148 offset:3072
	global_load_lds_dwordx4 v[242:243], off
	v_lshl_add_u64 v[242:243], v[240:241], 0, s[40:41]
	s_mov_b32 m0, s25
	s_nop 0
	global_load_lds_dwordx4 v[242:243], off
	s_barrier
	s_waitcnt lgkmcnt(0)
	s_waitcnt lgkmcnt(0)
	v_mfma_f32_16x16x32_bf16 v[94:97], v[218:221], v[172:175], v[94:97]
	v_mfma_f32_16x16x32_bf16 v[90:93], v[226:229], v[172:175], v[90:93]
	v_mfma_f32_16x16x32_bf16 v[86:89], v[218:221], v[180:183], v[86:89]
	v_mfma_f32_16x16x32_bf16 v[82:85], v[226:229], v[180:183], v[82:85]
	v_mfma_f32_16x16x32_bf16 v[78:81], v[218:221], v[188:191], v[78:81]
	v_mfma_f32_16x16x32_bf16 v[74:77], v[226:229], v[188:191], v[74:77]
	v_mfma_f32_16x16x32_bf16 v[70:73], v[218:221], v[196:199], v[70:73]
	v_mfma_f32_16x16x32_bf16 v[66:69], v[226:229], v[196:199], v[66:69]
	v_mfma_f32_16x16x32_bf16 v[94:97], v[222:225], v[176:179], v[94:97]
	v_mfma_f32_16x16x32_bf16 v[90:93], v[230:233], v[176:179], v[90:93]
	v_mfma_f32_16x16x32_bf16 v[86:89], v[222:225], v[184:187], v[86:89]
	v_mfma_f32_16x16x32_bf16 v[82:85], v[230:233], v[184:187], v[82:85]
	v_mfma_f32_16x16x32_bf16 v[78:81], v[222:225], v[192:195], v[78:81]
	v_mfma_f32_16x16x32_bf16 v[74:77], v[230:233], v[192:195], v[74:77]
	v_mfma_f32_16x16x32_bf16 v[70:73], v[222:225], v[200:203], v[70:73]
	v_mfma_f32_16x16x32_bf16 v[66:69], v[230:233], v[200:203], v[66:69]
	s_mov_b32 m0, s26
	v_lshl_add_u64 v[234:235], v[234:235], 0, s[40:41]
	s_barrier
	ds_read_b128 v[172:175], v147 offset:49152
	ds_read_b128 v[176:179], v147 offset:50176
	ds_read_b128 v[180:183], v153 offset:49152
	ds_read_b128 v[184:187], v153 offset:50176
	ds_read_b128 v[188:191], v154 offset:49152
	ds_read_b128 v[192:195], v154 offset:50176
	ds_read_b128 v[196:199], v155 offset:49152
	ds_read_b128 v[200:203], v155 offset:50176
	global_load_lds_dwordx4 v[234:235], off
	v_lshl_add_u64 v[234:235], v[236:237], 0, s[40:41]
	s_mov_b32 m0, s27
	s_nop 0
	global_load_lds_dwordx4 v[234:235], off
	s_barrier
;   #define STAGE(P,BASE,LD,br,kt) do{long _g=(long)(br)*LD+(long)(kt)*BK; \
;     _Pragma("unroll") for(int _i=0;_i<2;++_i){ \
;       __builtin_amdgcn_global_load_lds((const unsigned*)(BASE+_g+(long)sR[_i]*LD+sC[_i]), \
;         LDSP(unsigned,(char*)(P)+wid*1024+_i*8192),16,0,0);}}while(0)
;   #define LDA(dst,b,h) _Pragma("unroll") for(int m=0;m<4;++m) _Pragma("unroll") for(int k=0;k<2;++k) \
;     dst[m][k]=*reinterpret_cast<const s16x8*>((char*)SA(b,h)+lds_byte8(wr*64+m*16+fr,k*32+fq*8))
;   #define LDB(dst,b,h) _Pragma("unroll") for(int n=0;n<2;++n) _Pragma("unroll") for(int k=0;k<2;++k) \
;     dst[n][k]=*reinterpret_cast<const s16x8*>((char*)SB(b,h)+lds_byte8(wc*32+n*16+fr,k*32+fq*8))
;   #define MMA(ai,bj,At,Bt) do{__builtin_amdgcn_s_setprio(1); \
;     _Pragma("unroll") for(int m=0;m<4;++m) _Pragma("unroll") for(int n=0;n<2;++n) _Pragma("unroll") for(int k=0;k<2;++k) \
;       acc[ai][bj][m][n]=__builtin_amdgcn_mfma_f32_16x16x32_bf16(Bt[n][k],At[m][k],acc[ai][bj][m][n],0,0,0); \
;     __builtin_amdgcn_s_setprio(0);}while(0)
;   #define WAIT_V(n) asm volatile("s_waitcnt vmcnt(" #n ")":::"memory")
;   #define WAIT_L(n) asm volatile("s_waitcnt lgkmcnt(" #n ")":::"memory")
;   #define BAR __builtin_amdgcn_s_barrier()
; template <class Epi>
; __device__ __forceinline__ void gemm_tile8(const u16* __restrict__ A, long lda, const u16* __restrict__ Bt, long ldb, int K, char* shmc, Epi epi){
;     ...
;     STAGE(SB(1,1),Bt,ldb,bcol+HALF,t+3);
;     WAIT_V(6); BAR; MMA(1,1,At,B1); BAR;
;   }
;   { LDB(B0,0,0); LDA(At,0,0); STAGE(SA(1,1),A,lda,brow+HALF,nt-1);
;     BAR; WAIT_L(0); MMA(0,0,At,B0); BAR;
;     LDB(B1,0,1); BAR; WAIT_L(0); MMA(0,1,At,B1); BAR;
;     LDA(At,0,1); WAIT_V(4); BAR; WAIT_L(0); MMA(1,0,At,B0); MMA(1,1,At,B1); BAR; }
	s_waitcnt lgkmcnt(0)
	s_waitcnt lgkmcnt(0)
	v_mfma_f32_16x16x32_bf16 v[62:65], v[156:159], v[172:175], v[62:65]
	v_mfma_f32_16x16x32_bf16 v[58:61], v[164:167], v[172:175], v[58:61]
	v_mfma_f32_16x16x32_bf16 v[54:57], v[156:159], v[180:183], v[54:57]
	v_mfma_f32_16x16x32_bf16 v[50:53], v[164:167], v[180:183], v[50:53]
	v_mfma_f32_16x16x32_bf16 v[46:49], v[156:159], v[188:191], v[46:49]
	v_mfma_f32_16x16x32_bf16 v[42:45], v[164:167], v[188:191], v[42:45]
	v_mfma_f32_16x16x32_bf16 v[38:41], v[156:159], v[196:199], v[38:41]
	v_mfma_f32_16x16x32_bf16 v[34:37], v[164:167], v[196:199], v[34:37]
	v_mfma_f32_16x16x32_bf16 v[62:65], v[160:163], v[176:179], v[62:65]
	v_mfma_f32_16x16x32_bf16 v[58:61], v[168:171], v[176:179], v[58:61]
	v_mfma_f32_16x16x32_bf16 v[54:57], v[160:163], v[184:187], v[54:57]
	v_mfma_f32_16x16x32_bf16 v[50:53], v[168:171], v[184:187], v[50:53]
	v_mfma_f32_16x16x32_bf16 v[46:49], v[160:163], v[192:195], v[46:49]
	v_mfma_f32_16x16x32_bf16 v[42:45], v[168:171], v[192:195], v[42:45]
	v_mfma_f32_16x16x32_bf16 v[38:41], v[160:163], v[200:203], v[38:41]
	v_mfma_f32_16x16x32_bf16 v[34:37], v[168:171], v[200:203], v[34:37]
	s_barrier
	s_mov_b32 m0, s14
	v_lshl_add_u64 v[156:157], v[238:239], 0, s[42:43]
	global_load_lds_dwordx4 v[156:157], off
	v_lshl_add_u64 v[156:157], v[240:241], 0, s[42:43]
	s_mov_b32 m0, s15
	s_nop 0
	global_load_lds_dwordx4 v[156:157], off
	s_waitcnt vmcnt(6)
	s_barrier
	v_mfma_f32_16x16x32_bf16 v[28:31], v[218:221], v[172:175], v[28:31]
	v_mfma_f32_16x16x32_bf16 v[24:27], v[226:229], v[172:175], v[24:27]
	v_mfma_f32_16x16x32_bf16 v[20:23], v[218:221], v[180:183], v[20:23]
	v_mfma_f32_16x16x32_bf16 v[16:19], v[226:229], v[180:183], v[16:19]
	v_mfma_f32_16x16x32_bf16 v[12:15], v[218:221], v[188:191], v[12:15]
	v_mfma_f32_16x16x32_bf16 v[8:11], v[226:229], v[188:191], v[8:11]
	v_mfma_f32_16x16x32_bf16 v[4:7], v[218:221], v[196:199], v[4:7]
	v_mfma_f32_16x16x32_bf16 v[0:3], v[226:229], v[196:199], v[0:3]
	v_mfma_f32_16x16x32_bf16 v[28:31], v[222:225], v[176:179], v[28:31]
	v_mfma_f32_16x16x32_bf16 v[24:27], v[230:233], v[176:179], v[24:27]
	v_mfma_f32_16x16x32_bf16 v[20:23], v[222:225], v[184:187], v[20:23]
	v_mfma_f32_16x16x32_bf16 v[16:19], v[230:233], v[184:187], v[16:19]
	v_mfma_f32_16x16x32_bf16 v[12:15], v[222:225], v[192:195], v[12:15]
	v_mfma_f32_16x16x32_bf16 v[8:11], v[230:233], v[192:195], v[8:11]
	v_mfma_f32_16x16x32_bf16 v[4:7], v[222:225], v[200:203], v[4:7]
	v_mfma_f32_16x16x32_bf16 v[0:3], v[230:233], v[200:203], v[0:3]
	s_add_i32 s12, s12, 2
	s_add_u32 s10, s10, 0x100
	s_addc_u32 s11, s11, 0
	s_cmp_lt_u32 s12, 60
	s_barrier
	s_cbranch_scc1 .LBB0_963
	s_add_u32 s0, s0, 0x101f80
	s_addc_u32 s1, s1, 0
	v_lshl_add_u64 v[134:135], s[0:1], 0, v[134:135]
	s_mov_b32 m0, s31
	v_lshl_add_u64 v[130:131], v[130:131], 1, v[134:135]
	ds_read_b128 v[138:141], v152
	ds_read_b128 v[142:145], v152 offset:1024
	ds_read_b128 v[156:159], v152 offset:2048
	ds_read_b128 v[160:163], v152 offset:3072
	ds_read_b128 v[164:167], v147
	ds_read_b128 v[168:171], v147 offset:1024
	ds_read_b128 v[172:175], v153
	ds_read_b128 v[176:179], v153 offset:1024
	ds_read_b128 v[180:183], v154
	ds_read_b128 v[184:187], v154 offset:1024
	ds_read_b128 v[188:191], v155
	ds_read_b128 v[192:195], v155 offset:1024
	global_load_lds_dwordx4 v[130:131], off
	v_lshl_add_u64 v[130:131], s[0:1], 0, v[136:137]
	v_lshl_add_u64 v[130:131], v[132:133], 1, v[130:131]
	s_mov_b32 m0, s13
	s_nop 0
	global_load_lds_dwordx4 v[130:131], off
	s_barrier
	s_waitcnt lgkmcnt(0)
	s_waitcnt lgkmcnt(0)
	v_mfma_f32_16x16x32_bf16 v[126:129], v[138:141], v[164:167], v[126:129]
	v_mfma_f32_16x16x32_bf16 v[122:125], v[156:159], v[164:167], v[122:125]
	v_mfma_f32_16x16x32_bf16 v[118:121], v[138:141], v[172:175], v[118:121]
	v_mfma_f32_16x16x32_bf16 v[114:117], v[156:159], v[172:175], v[114:117]
	v_mfma_f32_16x16x32_bf16 v[110:113], v[138:141], v[180:183], v[110:113]
	v_mfma_f32_16x16x32_bf16 v[106:109], v[156:159], v[180:183], v[106:109]
	v_mfma_f32_16x16x32_bf16 v[102:105], v[138:141], v[188:191], v[102:105]
	v_mfma_f32_16x16x32_bf16 v[98:101], v[156:159], v[188:191], v[98:101]
	v_mfma_f32_16x16x32_bf16 v[126:129], v[142:145], v[168:171], v[126:129]
	v_mfma_f32_16x16x32_bf16 v[122:125], v[160:163], v[168:171], v[122:125]
	v_mfma_f32_16x16x32_bf16 v[118:121], v[142:145], v[176:179], v[118:121]
	v_mfma_f32_16x16x32_bf16 v[114:117], v[160:163], v[176:179], v[114:117]
	v_mfma_f32_16x16x32_bf16 v[110:113], v[142:145], v[184:187], v[110:113]
	v_mfma_f32_16x16x32_bf16 v[106:109], v[160:163], v[184:187], v[106:109]
	v_mfma_f32_16x16x32_bf16 v[102:105], v[142:145], v[192:195], v[102:105]
	v_mfma_f32_16x16x32_bf16 v[98:101], v[160:163], v[192:195], v[98:101]
	s_barrier
	ds_read_b128 v[130:133], v150
	ds_read_b128 v[134:137], v150 offset:1024
	ds_read_b128 v[196:199], v150 offset:2048
	ds_read_b128 v[200:203], v150 offset:3072
	s_barrier
	s_waitcnt lgkmcnt(0)
	s_waitcnt lgkmcnt(0)
	v_mfma_f32_16x16x32_bf16 v[94:97], v[130:133], v[164:167], v[94:97]
	v_mfma_f32_16x16x32_bf16 v[90:93], v[196:199], v[164:167], v[90:93]
	v_mfma_f32_16x16x32_bf16 v[86:89], v[130:133], v[172:175], v[86:89]
	v_mfma_f32_16x16x32_bf16 v[82:85], v[196:199], v[172:175], v[82:85]
	v_mfma_f32_16x16x32_bf16 v[78:81], v[130:133], v[180:183], v[78:81]
	v_mfma_f32_16x16x32_bf16 v[74:77], v[196:199], v[180:183], v[74:77]
	v_mfma_f32_16x16x32_bf16 v[70:73], v[130:133], v[188:191], v[70:73]
	v_mfma_f32_16x16x32_bf16 v[66:69], v[196:199], v[188:191], v[66:69]
	v_mfma_f32_16x16x32_bf16 v[94:97], v[134:137], v[168:171], v[94:97]
	v_mfma_f32_16x16x32_bf16 v[90:93], v[200:203], v[168:171], v[90:93]
	v_mfma_f32_16x16x32_bf16 v[86:89], v[134:137], v[176:179], v[86:89]
	v_mfma_f32_16x16x32_bf16 v[82:85], v[200:203], v[176:179], v[82:85]
	v_mfma_f32_16x16x32_bf16 v[78:81], v[134:137], v[184:187], v[78:81]
	v_mfma_f32_16x16x32_bf16 v[74:77], v[200:203], v[184:187], v[74:77]
	v_mfma_f32_16x16x32_bf16 v[70:73], v[134:137], v[192:195], v[70:73]
	v_mfma_f32_16x16x32_bf16 v[66:69], v[200:203], v[192:195], v[66:69]
	s_barrier
;   #define LDA(dst,b,h) _Pragma("unroll") for(int m=0;m<4;++m) _Pragma("unroll") for(int k=0;k<2;++k) \
;     dst[m][k]=*reinterpret_cast<const s16x8*>((char*)SA(b,h)+lds_byte8(wr*64+m*16+fr,k*32+fq*8))
;   #define LDB(dst,b,h) _Pragma("unroll") for(int n=0;n<2;++n) _Pragma("unroll") for(int k=0;k<2;++k) \
;     dst[n][k]=*reinterpret_cast<const s16x8*>((char*)SB(b,h)+lds_byte8(wc*32+n*16+fr,k*32+fq*8))
;   #define MMA(ai,bj,At,Bt) do{__builtin_amdgcn_s_setprio(1); \
;     _Pragma("unroll") for(int m=0;m<4;++m) _Pragma("unroll") for(int n=0;n<2;++n) _Pragma("unroll") for(int k=0;k<2;++k) \
;       acc[ai][bj][m][n]=__builtin_amdgcn_mfma_f32_16x16x32_bf16(Bt[n][k],At[m][k],acc[ai][bj][m][n],0,0,0); \
;     __builtin_amdgcn_s_setprio(0);}while(0)
;   #define WAIT_V(n) asm volatile("s_waitcnt vmcnt(" #n ")":::"memory")
;   #define WAIT_L(n) asm volatile("s_waitcnt lgkmcnt(" #n ")":::"memory")
;   #define BAR __builtin_amdgcn_s_barrier()
; template <class Epi>
; __device__ __forceinline__ void gemm_tile8(const u16* __restrict__ A, long lda, const u16* __restrict__ Bt, long ldb, int K, char* shmc, Epi epi){
;     ...
;     LDA(At,0,1); WAIT_V(4); BAR; WAIT_L(0); MMA(1,0,At,B0); MMA(1,1,At,B1); BAR; }
;   { LDB(B0,1,0); LDA(At,1,0); WAIT_V(2); BAR; WAIT_L(0); MMA(0,0,At,B0); BAR;
;     LDB(B1,1,1); WAIT_V(0); BAR; WAIT_L(0); MMA(0,1,At,B1); BAR;
	ds_read_b128 v[164:167], v147 offset:16384
	ds_read_b128 v[168:171], v147 offset:17408
	ds_read_b128 v[172:175], v153 offset:16384
	ds_read_b128 v[176:179], v153 offset:17408
	ds_read_b128 v[180:183], v154 offset:16384
	ds_read_b128 v[184:187], v154 offset:17408
	ds_read_b128 v[188:191], v155 offset:16384
	ds_read_b128 v[192:195], v155 offset:17408
	s_waitcnt vmcnt(4)
	s_barrier
	s_waitcnt lgkmcnt(0)
	s_waitcnt lgkmcnt(0)
	v_mfma_f32_16x16x32_bf16 v[62:65], v[138:141], v[164:167], v[62:65]
	v_mfma_f32_16x16x32_bf16 v[58:61], v[156:159], v[164:167], v[58:61]
	v_mfma_f32_16x16x32_bf16 v[54:57], v[138:141], v[172:175], v[54:57]
	v_mfma_f32_16x16x32_bf16 v[50:53], v[156:159], v[172:175], v[50:53]
	v_mfma_f32_16x16x32_bf16 v[46:49], v[138:141], v[180:183], v[46:49]
	v_mfma_f32_16x16x32_bf16 v[42:45], v[156:159], v[180:183], v[42:45]
	v_mfma_f32_16x16x32_bf16 v[38:41], v[138:141], v[188:191], v[38:41]
	v_mfma_f32_16x16x32_bf16 v[34:37], v[156:159], v[188:191], v[34:37]
	v_mfma_f32_16x16x32_bf16 v[62:65], v[142:145], v[168:171], v[62:65]
	v_mfma_f32_16x16x32_bf16 v[58:61], v[160:163], v[168:171], v[58:61]
	v_mfma_f32_16x16x32_bf16 v[54:57], v[142:145], v[176:179], v[54:57]
	v_mfma_f32_16x16x32_bf16 v[50:53], v[160:163], v[176:179], v[50:53]
	v_mfma_f32_16x16x32_bf16 v[46:49], v[142:145], v[184:187], v[46:49]
	v_mfma_f32_16x16x32_bf16 v[42:45], v[160:163], v[184:187], v[42:45]
	v_mfma_f32_16x16x32_bf16 v[38:41], v[142:145], v[192:195], v[38:41]
	v_mfma_f32_16x16x32_bf16 v[34:37], v[160:163], v[192:195], v[34:37]
	v_mfma_f32_16x16x32_bf16 v[28:31], v[130:133], v[164:167], v[28:31]
	v_mfma_f32_16x16x32_bf16 v[24:27], v[196:199], v[164:167], v[24:27]
	v_mfma_f32_16x16x32_bf16 v[20:23], v[130:133], v[172:175], v[20:23]
	v_mfma_f32_16x16x32_bf16 v[16:19], v[196:199], v[172:175], v[16:19]
	v_mfma_f32_16x16x32_bf16 v[12:15], v[130:133], v[180:183], v[12:15]
	v_mfma_f32_16x16x32_bf16 v[8:11], v[196:199], v[180:183], v[8:11]
	v_mfma_f32_16x16x32_bf16 v[4:7], v[130:133], v[188:191], v[4:7]
	v_mfma_f32_16x16x32_bf16 v[0:3], v[196:199], v[188:191], v[0:3]
	v_mfma_f32_16x16x32_bf16 v[28:31], v[134:137], v[168:171], v[28:31]
	v_mfma_f32_16x16x32_bf16 v[24:27], v[200:203], v[168:171], v[24:27]
	v_mfma_f32_16x16x32_bf16 v[20:23], v[134:137], v[176:179], v[20:23]
	v_mfma_f32_16x16x32_bf16 v[16:19], v[200:203], v[176:179], v[16:19]
	v_mfma_f32_16x16x32_bf16 v[12:15], v[134:137], v[184:187], v[12:15]
	v_mfma_f32_16x16x32_bf16 v[8:11], v[200:203], v[184:187], v[8:11]
	v_mfma_f32_16x16x32_bf16 v[4:7], v[134:137], v[192:195], v[4:7]
	v_mfma_f32_16x16x32_bf16 v[0:3], v[200:203], v[192:195], v[0:3]
	s_barrier
	ds_read_b128 v[130:133], v149
	ds_read_b128 v[134:137], v149 offset:1024
	ds_read_b128 v[138:141], v149 offset:2048
	ds_read_b128 v[142:145], v149 offset:3072
	ds_read_b128 v[156:159], v147 offset:32768
	ds_read_b128 v[160:163], v147 offset:33792
	ds_read_b128 v[164:167], v153 offset:32768
	ds_read_b128 v[168:171], v153 offset:33792
	ds_read_b128 v[172:175], v154 offset:32768
	ds_read_b128 v[176:179], v154 offset:33792
	ds_read_b128 v[180:183], v155 offset:32768
	ds_read_b128 v[184:187], v155 offset:33792
	s_waitcnt vmcnt(2)
	s_barrier
	s_waitcnt lgkmcnt(0)
	s_waitcnt lgkmcnt(0)
	v_mfma_f32_16x16x32_bf16 v[126:129], v[130:133], v[156:159], v[126:129]
	v_mfma_f32_16x16x32_bf16 v[122:125], v[138:141], v[156:159], v[122:125]
	v_mfma_f32_16x16x32_bf16 v[118:121], v[130:133], v[164:167], v[118:121]
	v_mfma_f32_16x16x32_bf16 v[114:117], v[138:141], v[164:167], v[114:117]
	v_mfma_f32_16x16x32_bf16 v[110:113], v[130:133], v[172:175], v[110:113]
	v_mfma_f32_16x16x32_bf16 v[106:109], v[138:141], v[172:175], v[106:109]
	v_mfma_f32_16x16x32_bf16 v[102:105], v[130:133], v[180:183], v[102:105]
	v_mfma_f32_16x16x32_bf16 v[98:101], v[138:141], v[180:183], v[98:101]
	v_mfma_f32_16x16x32_bf16 v[126:129], v[134:137], v[160:163], v[126:129]
	v_mfma_f32_16x16x32_bf16 v[122:125], v[142:145], v[160:163], v[122:125]
	v_mfma_f32_16x16x32_bf16 v[118:121], v[134:137], v[168:171], v[118:121]
	v_mfma_f32_16x16x32_bf16 v[114:117], v[142:145], v[168:171], v[114:117]
	v_mfma_f32_16x16x32_bf16 v[110:113], v[134:137], v[176:179], v[110:113]
	v_mfma_f32_16x16x32_bf16 v[106:109], v[142:145], v[176:179], v[106:109]
	v_mfma_f32_16x16x32_bf16 v[102:105], v[134:137], v[184:187], v[102:105]
	v_mfma_f32_16x16x32_bf16 v[98:101], v[142:145], v[184:187], v[98:101]
	s_barrier
;   #define LDA(dst,b,h) _Pragma("unroll") for(int m=0;m<4;++m) _Pragma("unroll") for(int k=0;k<2;++k) \
;     dst[m][k]=*reinterpret_cast<const s16x8*>((char*)SA(b,h)+lds_byte8(wr*64+m*16+fr,k*32+fq*8))
;   #define LDB(dst,b,h) _Pragma("unroll") for(int n=0;n<2;++n) _Pragma("unroll") for(int k=0;k<2;++k) \
;     dst[n][k]=*reinterpret_cast<const s16x8*>((char*)SB(b,h)+lds_byte8(wc*32+n*16+fr,k*32+fq*8))
;   #define MMA(ai,bj,At,Bt) do{__builtin_amdgcn_s_setprio(1); \
;     _Pragma("unroll") for(int m=0;m<4;++m) _Pragma("unroll") for(int n=0;n<2;++n) _Pragma("unroll") for(int k=0;k<2;++k) \
;       acc[ai][bj][m][n]=__builtin_amdgcn_mfma_f32_16x16x32_bf16(Bt[n][k],At[m][k],acc[ai][bj][m][n],0,0,0); \
;     __builtin_amdgcn_s_setprio(0);}while(0)
;   #define WAIT_V(n) asm volatile("s_waitcnt vmcnt(" #n ")":::"memory")
;   #define WAIT_L(n) asm volatile("s_waitcnt lgkmcnt(" #n ")":::"memory")
;   #define BAR __builtin_amdgcn_s_barrier()
; template <class Epi>
; __device__ __forceinline__ void gemm_tile8(const u16* __restrict__ A, long lda, const u16* __restrict__ Bt, long ldb, int K, char* shmc, Epi epi){
;     ...
;   { LDB(B0,1,0); LDA(At,1,0); WAIT_V(2); BAR; WAIT_L(0); MMA(0,0,At,B0); BAR;
;     LDB(B1,1,1); WAIT_V(0); BAR; WAIT_L(0); MMA(0,1,At,B1); BAR;
;     LDA(At,1,1); BAR; WAIT_L(0); MMA(1,0,At,B0); MMA(1,1,At,B1); BAR; }
;   if(wr==0)BAR;
	ds_read_b128 v[188:191], v148
	ds_read_b128 v[192:195], v148 offset:1024
	ds_read_b128 v[196:199], v148 offset:2048
	ds_read_b128 v[148:151], v148 offset:3072
	s_waitcnt vmcnt(0)
	s_barrier
	s_waitcnt lgkmcnt(0)
	s_waitcnt lgkmcnt(0)
	v_mfma_f32_16x16x32_bf16 v[94:97], v[188:191], v[156:159], v[94:97]
	v_mfma_f32_16x16x32_bf16 v[90:93], v[196:199], v[156:159], v[90:93]
	v_mfma_f32_16x16x32_bf16 v[86:89], v[188:191], v[164:167], v[86:89]
	v_mfma_f32_16x16x32_bf16 v[82:85], v[196:199], v[164:167], v[82:85]
	v_mfma_f32_16x16x32_bf16 v[78:81], v[188:191], v[172:175], v[78:81]
	v_mfma_f32_16x16x32_bf16 v[74:77], v[196:199], v[172:175], v[74:77]
	v_mfma_f32_16x16x32_bf16 v[70:73], v[188:191], v[180:183], v[70:73]
	v_mfma_f32_16x16x32_bf16 v[66:69], v[196:199], v[180:183], v[66:69]
	v_mfma_f32_16x16x32_bf16 v[94:97], v[192:195], v[160:163], v[94:97]
	v_mfma_f32_16x16x32_bf16 v[90:93], v[148:151], v[160:163], v[90:93]
	v_mfma_f32_16x16x32_bf16 v[86:89], v[192:195], v[168:171], v[86:89]
	v_mfma_f32_16x16x32_bf16 v[82:85], v[148:151], v[168:171], v[82:85]
	v_mfma_f32_16x16x32_bf16 v[78:81], v[192:195], v[176:179], v[78:81]
	v_mfma_f32_16x16x32_bf16 v[74:77], v[148:151], v[176:179], v[74:77]
	v_mfma_f32_16x16x32_bf16 v[70:73], v[192:195], v[184:187], v[70:73]
	v_mfma_f32_16x16x32_bf16 v[66:69], v[148:151], v[184:187], v[66:69]
	s_barrier
	ds_read_b128 v[156:159], v147 offset:49152
	ds_read_b128 v[160:163], v147 offset:50176
	ds_read_b128 v[164:167], v153 offset:49152
	ds_read_b128 v[168:171], v153 offset:50176
	ds_read_b128 v[172:175], v154 offset:49152
	ds_read_b128 v[176:179], v154 offset:50176
	ds_read_b128 v[180:183], v155 offset:49152
	ds_read_b128 v[152:155], v155 offset:50176
	s_barrier
	s_waitcnt lgkmcnt(0)
	s_waitcnt lgkmcnt(0)
	v_mfma_f32_16x16x32_bf16 v[62:65], v[130:133], v[156:159], v[62:65]
	v_mfma_f32_16x16x32_bf16 v[58:61], v[138:141], v[156:159], v[58:61]
	v_mfma_f32_16x16x32_bf16 v[54:57], v[130:133], v[164:167], v[54:57]
	v_mfma_f32_16x16x32_bf16 v[50:53], v[138:141], v[164:167], v[50:53]
	v_mfma_f32_16x16x32_bf16 v[46:49], v[130:133], v[172:175], v[46:49]
	v_mfma_f32_16x16x32_bf16 v[42:45], v[138:141], v[172:175], v[42:45]
	v_mfma_f32_16x16x32_bf16 v[38:41], v[130:133], v[180:183], v[38:41]
	v_mfma_f32_16x16x32_bf16 v[34:37], v[138:141], v[180:183], v[34:37]
	v_mfma_f32_16x16x32_bf16 v[62:65], v[134:137], v[160:163], v[62:65]
	v_mfma_f32_16x16x32_bf16 v[58:61], v[142:145], v[160:163], v[58:61]
	v_mfma_f32_16x16x32_bf16 v[54:57], v[134:137], v[168:171], v[54:57]
	v_mfma_f32_16x16x32_bf16 v[50:53], v[142:145], v[168:171], v[50:53]
	v_mfma_f32_16x16x32_bf16 v[46:49], v[134:137], v[176:179], v[46:49]
	v_mfma_f32_16x16x32_bf16 v[42:45], v[142:145], v[176:179], v[42:45]
	v_mfma_f32_16x16x32_bf16 v[38:41], v[134:137], v[152:155], v[38:41]
	v_mfma_f32_16x16x32_bf16 v[34:37], v[142:145], v[152:155], v[34:37]
	v_mfma_f32_16x16x32_bf16 v[28:31], v[188:191], v[156:159], v[28:31]
	v_mfma_f32_16x16x32_bf16 v[24:27], v[196:199], v[156:159], v[24:27]
	v_mfma_f32_16x16x32_bf16 v[20:23], v[188:191], v[164:167], v[20:23]
	v_mfma_f32_16x16x32_bf16 v[16:19], v[196:199], v[164:167], v[16:19]
	v_mfma_f32_16x16x32_bf16 v[12:15], v[188:191], v[172:175], v[12:15]
	v_mfma_f32_16x16x32_bf16 v[8:11], v[196:199], v[172:175], v[8:11]
	v_mfma_f32_16x16x32_bf16 v[4:7], v[188:191], v[180:183], v[4:7]
	v_mfma_f32_16x16x32_bf16 v[0:3], v[196:199], v[180:183], v[0:3]
	v_mfma_f32_16x16x32_bf16 v[28:31], v[192:195], v[160:163], v[28:31]
	v_mfma_f32_16x16x32_bf16 v[24:27], v[148:151], v[160:163], v[24:27]
	v_mfma_f32_16x16x32_bf16 v[20:23], v[192:195], v[168:171], v[20:23]
	v_mfma_f32_16x16x32_bf16 v[16:19], v[148:151], v[168:171], v[16:19]
	v_mfma_f32_16x16x32_bf16 v[12:15], v[192:195], v[176:179], v[12:15]
	v_mfma_f32_16x16x32_bf16 v[8:11], v[148:151], v[176:179], v[8:11]
	v_mfma_f32_16x16x32_bf16 v[4:7], v[192:195], v[152:155], v[4:7]
	v_mfma_f32_16x16x32_bf16 v[0:3], v[148:151], v[152:155], v[0:3]
	s_cmpk_gt_u32 s7, 0xff
	s_barrier
	s_cbranch_scc1 .LBB0_966
	s_barrier
